# GEMM K-loops: mid-cluster s_setprio 0/1 pair and the redundant post-barrier lgkmcnt(0) removed from every 32-MFMA cluster (3 fewer issue slots per cluster)
# speedup vs baseline: 1.0061x; 1.0061x over previous
; #define PG8_STAGE(bufoff, gbase, voff) do { _Pragma("unroll") for (int _i = 0; _i < 2; ++_i) \
;         __builtin_amdgcn_global_load_lds((const unsigned*)((const char*)(gbase) + (voff)[_i]), (PG8_LAS unsigned*)(lds + (bufoff) + ldsw + _i * 8192), 16, 0, 0); } while (0)
; #define PG8_LDA(dst, b, h) do { _Pragma("unroll") for (int m = 0; m < 4; ++m) _Pragma("unroll") for (int k = 0; k < 2; ++k) dst[m][k] = *(const PG8_LAS bf16x8*)(lds + PG8_SA(b, h) + aoff + m * 2048 + k * 1024); } while (0)
; #define PG8_LDB(dst, b, h) do { _Pragma("unroll") for (int n = 0; n < 2; ++n) _Pragma("unroll") for (int k = 0; k < 2; ++k) dst[n][k] = *(const PG8_LAS bf16x8*)(lds + PG8_SB(b, h) + boff + n * 2048 + k * 1024); } while (0)
; #define PG8_MMA(ai, bj, At, Bt) do { __builtin_amdgcn_s_setprio(1); _Pragma("unroll") for (int m = 0; m < 4; ++m) _Pragma("unroll") for (int n = 0; n < 2; ++n) _Pragma("unroll") for (int k = 0; k < 2; ++k) \
;         acc[ai][bj][m][n] = mma16<Epi::F16>(Bt[n][k], At[m][k], acc[ai][bj][m][n]); __builtin_amdgcn_s_setprio(0); } while (0)
; #define PG8_WAIT_V(n) asm volatile("s_waitcnt vmcnt(" #n ")" ::: "memory")
; #define PG8_WAIT_L(n) asm volatile("s_waitcnt lgkmcnt(" #n ")" ::: "memory")
; template <class Epi, class Sched, bool ALIGN_EPI = false, bool SP2 = false>
; __device__ __forceinline__ void gemm_phase(PG8_LAS unsigned char* lds, const Gemm g, const Sched& S, const Epi& E, const int wave_in) {
;     ...
;         for (int t = 0; t < nt; t += 2) {
;             const bool last = (t == nt - 2);
;             const char* a1 = cA + (size_t)(t + 1) * kstep;
;             const char* a2 = last ? nA : cA + (size_t)(t + 2) * kstep; const char* b2 = last ? nB : cB + (size_t)(t + 2) * kstep;
;             const char* a3 = a2 + kstep; const char* b3 = b2 + kstep;
;             if (last && has_next) S.a_ready(nxt);
;             if constexpr (SP2) {
;             PG8_LDB(B0, 0, 0); PG8_LDB(B1, 0, 1); PG8_SCHED; PG8_LDA(At, 0, 0); PG8_STAGE(PG8_SA(1, 1), a1 + hstep, voffA);
;             PG8_WAIT_V(8); PG8_WAIT_L(0); PG8_BAR; PG8_MMA(0, 0, At, B0); PG8_MMA(0, 1, At, B1); PG8_BAR; PG8_SCHED;
;             PG8_LDA(At, 0, 1); PG8_STAGE(PG8_SB(0, 0), b2, voffB); PG8_STAGE(PG8_SB(0, 1), b2 + hstep, voffB); PG8_STAGE(PG8_SA(0, 0), a2, voffA);
;             PG8_WAIT_V(8); PG8_WAIT_L(0); PG8_BAR; PG8_MMA(1, 0, At, B0); PG8_MMA(1, 1, At, B1); PG8_BAR; PG8_SCHED;
.LBB0_320:
	s_add_u32 s14, s38, 0xfffc0080
	s_addc_u32 s15, s39, -1
	s_cmp_eq_u32 s76, 12
	s_cselect_b32 s91, s10, s15
	s_cselect_b32 s90, s11, s14
	s_cselect_b32 s37, s59, s13
	s_cselect_b32 s36, s61, s12
	s_add_i32 s72, 0, 0x14000
	v_add_u32_e32 v154, s72, v179
	ds_read_b128 v[114:117], v185
	ds_read_b128 v[118:121], v185 offset:1024
	ds_read_b128 v[122:125], v185 offset:2048
	ds_read_b128 v[130:133], v185 offset:3072
	ds_read_b128 v[138:141], v154
	ds_read_b128 v[142:145], v154 offset:1024
	ds_read_b128 v[146:149], v154 offset:2048
	ds_read_b128 v[154:157], v154 offset:3072
	v_lshl_add_u64 v[216:217], s[38:39], 0, v[168:169]
	s_add_i32 m0, s1, 0xc000
	ds_read_b128 v[172:175], v183
	ds_read_b128 v[186:189], v183 offset:1024
	ds_read_b128 v[190:193], v183 offset:2048
	ds_read_b128 v[194:197], v183 offset:3072
	ds_read_b128 v[198:201], v183 offset:4096
	ds_read_b128 v[202:205], v183 offset:5120
	ds_read_b128 v[208:211], v183 offset:6144
	ds_read_b128 v[212:215], v183 offset:7168
	global_load_lds_dwordx4 v[216:217], off
	v_lshl_add_u64 v[216:217], s[38:39], 0, v[170:171]
	s_add_i32 m0, s1, 0xe000
	s_nop 0
	global_load_lds_dwordx4 v[216:217], off
	s_waitcnt vmcnt(8)
	s_waitcnt lgkmcnt(0)
	s_barrier
	s_setprio 1
	v_mfma_f32_16x16x32_f16 v[158:161], v[114:117], v[172:175], v[158:161]
	v_mfma_f32_16x16x32_f16 v[150:153], v[122:125], v[172:175], v[150:153]
	v_mfma_f32_16x16x32_f16 v[110:113], v[114:117], v[190:193], v[110:113]
	v_mfma_f32_16x16x32_f16 v[106:109], v[122:125], v[190:193], v[106:109]
	v_mfma_f32_16x16x32_f16 v[94:97], v[114:117], v[198:201], v[94:97]
	v_mfma_f32_16x16x32_f16 v[90:93], v[122:125], v[198:201], v[90:93]
	v_mfma_f32_16x16x32_f16 v[78:81], v[114:117], v[208:211], v[78:81]
	v_mfma_f32_16x16x32_f16 v[74:77], v[122:125], v[208:211], v[74:77]
	v_mfma_f32_16x16x32_f16 v[158:161], v[118:121], v[186:189], v[158:161]
	v_mfma_f32_16x16x32_f16 v[150:153], v[130:133], v[186:189], v[150:153]
	v_mfma_f32_16x16x32_f16 v[110:113], v[118:121], v[194:197], v[110:113]
	v_mfma_f32_16x16x32_f16 v[106:109], v[130:133], v[194:197], v[106:109]
	v_mfma_f32_16x16x32_f16 v[94:97], v[118:121], v[202:205], v[94:97]
	v_mfma_f32_16x16x32_f16 v[90:93], v[130:133], v[202:205], v[90:93]
	v_mfma_f32_16x16x32_f16 v[78:81], v[118:121], v[212:215], v[78:81]
	v_mfma_f32_16x16x32_f16 v[74:77], v[130:133], v[212:215], v[74:77]
	v_mfma_f32_16x16x32_f16 v[134:137], v[138:141], v[172:175], v[134:137]
	v_mfma_f32_16x16x32_f16 v[126:129], v[146:149], v[172:175], v[126:129]
	v_mfma_f32_16x16x32_f16 v[102:105], v[138:141], v[190:193], v[102:105]
	v_mfma_f32_16x16x32_f16 v[98:101], v[146:149], v[190:193], v[98:101]
	v_mfma_f32_16x16x32_f16 v[86:89], v[138:141], v[198:201], v[86:89]
	v_mfma_f32_16x16x32_f16 v[82:85], v[146:149], v[198:201], v[82:85]
	v_mfma_f32_16x16x32_f16 v[70:73], v[138:141], v[208:211], v[70:73]
	v_mfma_f32_16x16x32_f16 v[66:69], v[146:149], v[208:211], v[66:69]
	v_mfma_f32_16x16x32_f16 v[134:137], v[142:145], v[186:189], v[134:137]
	v_mfma_f32_16x16x32_f16 v[126:129], v[154:157], v[186:189], v[126:129]
	v_mfma_f32_16x16x32_f16 v[102:105], v[142:145], v[194:197], v[102:105]
	v_mfma_f32_16x16x32_f16 v[98:101], v[154:157], v[194:197], v[98:101]
	v_mfma_f32_16x16x32_f16 v[86:89], v[142:145], v[202:205], v[86:89]
	v_mfma_f32_16x16x32_f16 v[82:85], v[154:157], v[202:205], v[82:85]
	v_mfma_f32_16x16x32_f16 v[70:73], v[142:145], v[212:215], v[70:73]
	v_mfma_f32_16x16x32_f16 v[66:69], v[154:157], v[212:215], v[66:69]
	s_setprio 0
	s_barrier
	s_add_i32 s14, s28, s0
	v_lshl_add_u64 v[216:217], s[36:37], 0, v[0:1]
	s_mov_b32 m0, s14
	ds_read_b128 v[172:175], v183 offset:16384
	ds_read_b128 v[186:189], v183 offset:17408
	ds_read_b128 v[190:193], v183 offset:18432
	ds_read_b128 v[194:197], v183 offset:19456
	ds_read_b128 v[198:201], v183 offset:20480
	ds_read_b128 v[202:205], v183 offset:21504
	ds_read_b128 v[208:211], v183 offset:22528
	ds_read_b128 v[212:215], v183 offset:23552
	global_load_lds_dwordx4 v[216:217], off
	s_add_i32 m0, s14, 0x2000
	s_add_u32 s82, s36, 0x40000
	v_lshl_add_u64 v[218:219], s[36:37], 0, v[166:167]
	s_addc_u32 s83, s37, 0
	s_add_i32 s14, s72, s0
	global_load_lds_dwordx4 v[218:219], off
	v_lshl_add_u64 v[220:221], s[82:83], 0, v[0:1]
	s_mov_b32 m0, s14
	v_lshl_add_u64 v[222:223], s[90:91], 0, v[164:165]
	global_load_lds_dwordx4 v[220:221], off
	v_lshl_add_u64 v[220:221], s[82:83], 0, v[166:167]
	s_add_i32 m0, s14, 0x2000
	s_nop 0
	global_load_lds_dwordx4 v[220:221], off
	v_lshl_add_u64 v[220:221], s[90:91], 0, v[162:163]
	s_mov_b32 m0, s1
	s_nop 0
	global_load_lds_dwordx4 v[220:221], off
	s_mov_b32 m0, s4
	s_nop 0
	global_load_lds_dwordx4 v[222:223], off
	s_waitcnt vmcnt(8)
	s_waitcnt lgkmcnt(0)
	s_barrier
; #define PG8_STAGE(bufoff, gbase, voff) do { _Pragma("unroll") for (int _i = 0; _i < 2; ++_i) \
;         __builtin_amdgcn_global_load_lds((const unsigned*)((const char*)(gbase) + (voff)[_i]), (PG8_LAS unsigned*)(lds + (bufoff) + ldsw + _i * 8192), 16, 0, 0); } while (0)
; #define PG8_LDA(dst, b, h) do { _Pragma("unroll") for (int m = 0; m < 4; ++m) _Pragma("unroll") for (int k = 0; k < 2; ++k) dst[m][k] = *(const PG8_LAS bf16x8*)(lds + PG8_SA(b, h) + aoff + m * 2048 + k * 1024); } while (0)
; #define PG8_LDB(dst, b, h) do { _Pragma("unroll") for (int n = 0; n < 2; ++n) _Pragma("unroll") for (int k = 0; k < 2; ++k) dst[n][k] = *(const PG8_LAS bf16x8*)(lds + PG8_SB(b, h) + boff + n * 2048 + k * 1024); } while (0)
; #define PG8_MMA(ai, bj, At, Bt) do { __builtin_amdgcn_s_setprio(1); _Pragma("unroll") for (int m = 0; m < 4; ++m) _Pragma("unroll") for (int n = 0; n < 2; ++n) _Pragma("unroll") for (int k = 0; k < 2; ++k) \
;         acc[ai][bj][m][n] = mma16<Epi::F16>(Bt[n][k], At[m][k], acc[ai][bj][m][n]); __builtin_amdgcn_s_setprio(0); } while (0)
; #define PG8_WAIT_V(n) asm volatile("s_waitcnt vmcnt(" #n ")" ::: "memory")
; #define PG8_WAIT_L(n) asm volatile("s_waitcnt lgkmcnt(" #n ")" ::: "memory")
; #define PG8_BAR __builtin_amdgcn_s_barrier()
; #define PG8_SCHED __builtin_amdgcn_sched_barrier(0)
; template <class Epi, class Sched, bool ALIGN_EPI = false, bool SP2 = false>
; __device__ __forceinline__ void gemm_phase(PG8_LAS unsigned char* lds, const Gemm g, const Sched& S, const Epi& E, const int wave_in) {
;     ...
;             PG8_WAIT_V(8); PG8_WAIT_L(0); PG8_BAR; PG8_MMA(1, 0, At, B0); PG8_MMA(1, 1, At, B1); PG8_BAR; PG8_SCHED;
;             PG8_LDB(B0, 1, 0); PG8_LDB(B1, 1, 1); PG8_SCHED; PG8_LDA(At, 1, 0); PG8_STAGE(PG8_SA(0, 1), a2 + hstep, voffA);
;             PG8_WAIT_V(8); PG8_WAIT_L(0); PG8_BAR; PG8_MMA(0, 0, At, B0); PG8_MMA(0, 1, At, B1); PG8_BAR; PG8_SCHED;
	s_setprio 1
	v_mfma_f32_16x16x32_f16 v[62:65], v[114:117], v[172:175], v[62:65]
	v_mfma_f32_16x16x32_f16 v[58:61], v[122:125], v[172:175], v[58:61]
	v_mfma_f32_16x16x32_f16 v[46:49], v[114:117], v[190:193], v[46:49]
	v_mfma_f32_16x16x32_f16 v[42:45], v[122:125], v[190:193], v[42:45]
	v_mfma_f32_16x16x32_f16 v[30:33], v[114:117], v[198:201], v[30:33]
	v_mfma_f32_16x16x32_f16 v[26:29], v[122:125], v[198:201], v[26:29]
	v_mfma_f32_16x16x32_f16 v[14:17], v[114:117], v[208:211], v[14:17]
	v_mfma_f32_16x16x32_f16 v[10:13], v[122:125], v[208:211], v[10:13]
	v_mfma_f32_16x16x32_f16 v[62:65], v[118:121], v[186:189], v[62:65]
	v_mfma_f32_16x16x32_f16 v[58:61], v[130:133], v[186:189], v[58:61]
	v_mfma_f32_16x16x32_f16 v[46:49], v[118:121], v[194:197], v[46:49]
	v_mfma_f32_16x16x32_f16 v[42:45], v[130:133], v[194:197], v[42:45]
	v_mfma_f32_16x16x32_f16 v[30:33], v[118:121], v[202:205], v[30:33]
	v_mfma_f32_16x16x32_f16 v[26:29], v[130:133], v[202:205], v[26:29]
	v_mfma_f32_16x16x32_f16 v[14:17], v[118:121], v[212:215], v[14:17]
	v_mfma_f32_16x16x32_f16 v[10:13], v[130:133], v[212:215], v[10:13]
	v_mfma_f32_16x16x32_f16 v[54:57], v[138:141], v[172:175], v[54:57]
	v_mfma_f32_16x16x32_f16 v[50:53], v[146:149], v[172:175], v[50:53]
	v_mfma_f32_16x16x32_f16 v[38:41], v[138:141], v[190:193], v[38:41]
	v_mfma_f32_16x16x32_f16 v[34:37], v[146:149], v[190:193], v[34:37]
	v_mfma_f32_16x16x32_f16 v[22:25], v[138:141], v[198:201], v[22:25]
	v_mfma_f32_16x16x32_f16 v[18:21], v[146:149], v[198:201], v[18:21]
	v_mfma_f32_16x16x32_f16 v[6:9], v[138:141], v[208:211], v[6:9]
	v_mfma_f32_16x16x32_f16 v[2:5], v[146:149], v[208:211], v[2:5]
	v_mfma_f32_16x16x32_f16 v[54:57], v[142:145], v[186:189], v[54:57]
	v_mfma_f32_16x16x32_f16 v[50:53], v[154:157], v[186:189], v[50:53]
	v_mfma_f32_16x16x32_f16 v[38:41], v[142:145], v[194:197], v[38:41]
	v_mfma_f32_16x16x32_f16 v[34:37], v[154:157], v[194:197], v[34:37]
	v_mfma_f32_16x16x32_f16 v[22:25], v[142:145], v[202:205], v[22:25]
	v_mfma_f32_16x16x32_f16 v[18:21], v[154:157], v[202:205], v[18:21]
	v_mfma_f32_16x16x32_f16 v[6:9], v[142:145], v[212:215], v[6:9]
	v_mfma_f32_16x16x32_f16 v[2:5], v[154:157], v[212:215], v[2:5]
	s_setprio 0
	s_barrier
	s_add_i32 s73, 0, 0x18000
	s_add_i32 s74, 0, 0x1c000
	v_add_u32_e32 v130, s73, v179
	v_add_u32_e32 v154, s74, v179
	ds_read_b128 v[114:117], v130
	ds_read_b128 v[118:121], v130 offset:1024
	ds_read_b128 v[122:125], v130 offset:2048
	ds_read_b128 v[130:133], v130 offset:3072
	ds_read_b128 v[138:141], v154
	ds_read_b128 v[142:145], v154 offset:1024
	ds_read_b128 v[146:149], v154 offset:2048
	ds_read_b128 v[154:157], v154 offset:3072
	s_add_u32 s82, s90, 0x40000
	s_addc_u32 s83, s91, 0
	s_mov_b32 m0, s5
	v_lshl_add_u64 v[224:225], s[82:83], 0, v[162:163]
	ds_read_b128 v[172:175], v183 offset:32768
	ds_read_b128 v[186:189], v183 offset:33792
	ds_read_b128 v[190:193], v183 offset:34816
	ds_read_b128 v[194:197], v183 offset:35840
	ds_read_b128 v[198:201], v183 offset:36864
	ds_read_b128 v[202:205], v183 offset:37888
	ds_read_b128 v[208:211], v183 offset:38912
	ds_read_b128 v[212:215], v183 offset:39936
	global_load_lds_dwordx4 v[224:225], off
	v_lshl_add_u64 v[224:225], s[82:83], 0, v[164:165]
	s_mov_b32 m0, s6
	s_nop 0
	global_load_lds_dwordx4 v[224:225], off
	s_waitcnt vmcnt(8)
	s_waitcnt lgkmcnt(0)
	s_barrier
	s_setprio 1
	v_mfma_f32_16x16x32_f16 v[158:161], v[114:117], v[172:175], v[158:161]
	v_mfma_f32_16x16x32_f16 v[150:153], v[122:125], v[172:175], v[150:153]
	v_mfma_f32_16x16x32_f16 v[110:113], v[114:117], v[190:193], v[110:113]
	v_mfma_f32_16x16x32_f16 v[106:109], v[122:125], v[190:193], v[106:109]
	v_mfma_f32_16x16x32_f16 v[94:97], v[114:117], v[198:201], v[94:97]
	v_mfma_f32_16x16x32_f16 v[90:93], v[122:125], v[198:201], v[90:93]
	v_mfma_f32_16x16x32_f16 v[78:81], v[114:117], v[208:211], v[78:81]
	v_mfma_f32_16x16x32_f16 v[74:77], v[122:125], v[208:211], v[74:77]
	v_mfma_f32_16x16x32_f16 v[158:161], v[118:121], v[186:189], v[158:161]
	v_mfma_f32_16x16x32_f16 v[150:153], v[130:133], v[186:189], v[150:153]
	v_mfma_f32_16x16x32_f16 v[110:113], v[118:121], v[194:197], v[110:113]
	v_mfma_f32_16x16x32_f16 v[106:109], v[130:133], v[194:197], v[106:109]
	v_mfma_f32_16x16x32_f16 v[94:97], v[118:121], v[202:205], v[94:97]
	v_mfma_f32_16x16x32_f16 v[90:93], v[130:133], v[202:205], v[90:93]
	v_mfma_f32_16x16x32_f16 v[78:81], v[118:121], v[212:215], v[78:81]
	v_mfma_f32_16x16x32_f16 v[74:77], v[130:133], v[212:215], v[74:77]
	v_mfma_f32_16x16x32_f16 v[134:137], v[138:141], v[172:175], v[134:137]
	v_mfma_f32_16x16x32_f16 v[126:129], v[146:149], v[172:175], v[126:129]
	v_mfma_f32_16x16x32_f16 v[102:105], v[138:141], v[190:193], v[102:105]
	v_mfma_f32_16x16x32_f16 v[98:101], v[146:149], v[190:193], v[98:101]
	v_mfma_f32_16x16x32_f16 v[86:89], v[138:141], v[198:201], v[86:89]
	v_mfma_f32_16x16x32_f16 v[82:85], v[146:149], v[198:201], v[82:85]
	v_mfma_f32_16x16x32_f16 v[70:73], v[138:141], v[208:211], v[70:73]
	v_mfma_f32_16x16x32_f16 v[66:69], v[146:149], v[208:211], v[66:69]
	v_mfma_f32_16x16x32_f16 v[134:137], v[142:145], v[186:189], v[134:137]
	v_mfma_f32_16x16x32_f16 v[126:129], v[154:157], v[186:189], v[126:129]
	v_mfma_f32_16x16x32_f16 v[102:105], v[142:145], v[194:197], v[102:105]
	v_mfma_f32_16x16x32_f16 v[98:101], v[154:157], v[194:197], v[98:101]
	v_mfma_f32_16x16x32_f16 v[86:89], v[142:145], v[202:205], v[86:89]
	v_mfma_f32_16x16x32_f16 v[82:85], v[154:157], v[202:205], v[82:85]
	v_mfma_f32_16x16x32_f16 v[70:73], v[142:145], v[212:215], v[70:73]
	v_mfma_f32_16x16x32_f16 v[66:69], v[154:157], v[212:215], v[66:69]
	s_setprio 0
	s_barrier
; #define PG8_STAGE(bufoff, gbase, voff) do { _Pragma("unroll") for (int _i = 0; _i < 2; ++_i) \
;         __builtin_amdgcn_global_load_lds((const unsigned*)((const char*)(gbase) + (voff)[_i]), (PG8_LAS unsigned*)(lds + (bufoff) + ldsw + _i * 8192), 16, 0, 0); } while (0)
; #define PG8_LDA(dst, b, h) do { _Pragma("unroll") for (int m = 0; m < 4; ++m) _Pragma("unroll") for (int k = 0; k < 2; ++k) dst[m][k] = *(const PG8_LAS bf16x8*)(lds + PG8_SA(b, h) + aoff + m * 2048 + k * 1024); } while (0)
; #define PG8_MMA(ai, bj, At, Bt) do { __builtin_amdgcn_s_setprio(1); _Pragma("unroll") for (int m = 0; m < 4; ++m) _Pragma("unroll") for (int n = 0; n < 2; ++n) _Pragma("unroll") for (int k = 0; k < 2; ++k) \
;         acc[ai][bj][m][n] = mma16<Epi::F16>(Bt[n][k], At[m][k], acc[ai][bj][m][n]); __builtin_amdgcn_s_setprio(0); } while (0)
; #define PG8_WAIT_V(n) asm volatile("s_waitcnt vmcnt(" #n ")" ::: "memory")
; #define PG8_WAIT_L(n) asm volatile("s_waitcnt lgkmcnt(" #n ")" ::: "memory")
; #define PG8_BAR __builtin_amdgcn_s_barrier()
; #define PG8_SCHED __builtin_amdgcn_sched_barrier(0)
; template <class Epi, class Sched, bool ALIGN_EPI = false, bool SP2 = false>
; __device__ __forceinline__ void gemm_phase(PG8_LAS unsigned char* lds, const Gemm g, const Sched& S, const Epi& E, const int wave_in) {
;     ...
;         for (int t = 0; t < nt; t += 2) {
;             const bool last = (t == nt - 2);
;             const char* a1 = cA + (size_t)(t + 1) * kstep;
;             const char* a2 = last ? nA : cA + (size_t)(t + 2) * kstep; const char* b2 = last ? nB : cB + (size_t)(t + 2) * kstep;
;             const char* a3 = a2 + kstep; const char* b3 = b2 + kstep;
;             if (last && has_next) S.a_ready(nxt);
;     ...
;             PG8_LDA(At, 1, 1); PG8_STAGE(PG8_SB(1, 0), b3, voffB); PG8_STAGE(PG8_SB(1, 1), b3 + hstep, voffB); PG8_STAGE(PG8_SA(1, 0), a3, voffA);
;             PG8_WAIT_V(8); PG8_WAIT_L(0); PG8_BAR; PG8_MMA(1, 0, At, B0); PG8_MMA(1, 1, At, B1); PG8_BAR; PG8_SCHED;
	s_add_i32 s14, s73, s0
	v_lshl_add_u64 v[216:217], v[216:217], 0, s[78:79]
	s_mov_b32 m0, s14
	ds_read_b128 v[172:175], v183 offset:49152
	ds_read_b128 v[186:189], v183 offset:50176
	ds_read_b128 v[190:193], v183 offset:51200
	ds_read_b128 v[194:197], v183 offset:52224
	ds_read_b128 v[198:201], v183 offset:53248
	ds_read_b128 v[202:205], v183 offset:54272
	ds_read_b128 v[208:211], v183 offset:55296
	ds_read_b128 v[212:215], v183 offset:56320
	global_load_lds_dwordx4 v[216:217], off
	s_add_i32 m0, s14, 0x2000
	s_add_u32 s36, s36, 0x40080
	v_lshl_add_u64 v[216:217], v[218:219], 0, s[78:79]
	s_addc_u32 s37, s37, 0
	s_add_i32 s14, s74, s0
	global_load_lds_dwordx4 v[216:217], off
	v_lshl_add_u64 v[216:217], s[36:37], 0, v[0:1]
	s_mov_b32 m0, s14
	s_nop 0
	global_load_lds_dwordx4 v[216:217], off
	v_lshl_add_u64 v[216:217], s[36:37], 0, v[166:167]
	s_add_i32 m0, s14, 0x2000
	s_nop 0
	global_load_lds_dwordx4 v[216:217], off
	v_lshl_add_u64 v[216:217], v[220:221], 0, s[78:79]
	s_mov_b32 m0, s7
	s_nop 0
	global_load_lds_dwordx4 v[216:217], off
	v_lshl_add_u64 v[216:217], v[222:223], 0, s[78:79]
	s_mov_b32 m0, s8
	s_nop 0
	global_load_lds_dwordx4 v[216:217], off
	s_waitcnt vmcnt(8)
	s_waitcnt lgkmcnt(0)
	s_barrier
	s_setprio 1
	v_mfma_f32_16x16x32_f16 v[62:65], v[114:117], v[172:175], v[62:65]
	v_mfma_f32_16x16x32_f16 v[58:61], v[122:125], v[172:175], v[58:61]
	v_mfma_f32_16x16x32_f16 v[46:49], v[114:117], v[190:193], v[46:49]
	v_mfma_f32_16x16x32_f16 v[42:45], v[122:125], v[190:193], v[42:45]
	v_mfma_f32_16x16x32_f16 v[30:33], v[114:117], v[198:201], v[30:33]
	v_mfma_f32_16x16x32_f16 v[26:29], v[122:125], v[198:201], v[26:29]
	v_mfma_f32_16x16x32_f16 v[14:17], v[114:117], v[208:211], v[14:17]
	v_mfma_f32_16x16x32_f16 v[10:13], v[122:125], v[208:211], v[10:13]
	v_mfma_f32_16x16x32_f16 v[62:65], v[118:121], v[186:189], v[62:65]
	v_mfma_f32_16x16x32_f16 v[58:61], v[130:133], v[186:189], v[58:61]
	v_mfma_f32_16x16x32_f16 v[46:49], v[118:121], v[194:197], v[46:49]
	v_mfma_f32_16x16x32_f16 v[42:45], v[130:133], v[194:197], v[42:45]
	v_mfma_f32_16x16x32_f16 v[30:33], v[118:121], v[202:205], v[30:33]
	v_mfma_f32_16x16x32_f16 v[26:29], v[130:133], v[202:205], v[26:29]
	v_mfma_f32_16x16x32_f16 v[14:17], v[118:121], v[212:215], v[14:17]
	v_mfma_f32_16x16x32_f16 v[10:13], v[130:133], v[212:215], v[10:13]
	v_mfma_f32_16x16x32_f16 v[54:57], v[138:141], v[172:175], v[54:57]
	v_mfma_f32_16x16x32_f16 v[50:53], v[146:149], v[172:175], v[50:53]
	v_mfma_f32_16x16x32_f16 v[38:41], v[138:141], v[190:193], v[38:41]
	v_mfma_f32_16x16x32_f16 v[34:37], v[146:149], v[190:193], v[34:37]
	v_mfma_f32_16x16x32_f16 v[22:25], v[138:141], v[198:201], v[22:25]
	v_mfma_f32_16x16x32_f16 v[18:21], v[146:149], v[198:201], v[18:21]
	v_mfma_f32_16x16x32_f16 v[6:9], v[138:141], v[208:211], v[6:9]
	v_mfma_f32_16x16x32_f16 v[2:5], v[146:149], v[208:211], v[2:5]
	v_mfma_f32_16x16x32_f16 v[54:57], v[142:145], v[186:189], v[54:57]
	v_mfma_f32_16x16x32_f16 v[50:53], v[154:157], v[186:189], v[50:53]
	v_mfma_f32_16x16x32_f16 v[38:41], v[142:145], v[194:197], v[38:41]
	v_mfma_f32_16x16x32_f16 v[34:37], v[154:157], v[194:197], v[34:37]
	v_mfma_f32_16x16x32_f16 v[22:25], v[142:145], v[202:205], v[22:25]
	v_mfma_f32_16x16x32_f16 v[18:21], v[154:157], v[202:205], v[18:21]
	v_mfma_f32_16x16x32_f16 v[6:9], v[142:145], v[212:215], v[6:9]
	v_mfma_f32_16x16x32_f16 v[2:5], v[154:157], v[212:215], v[2:5]
	s_setprio 0
	s_barrier
	s_add_i32 s76, s76, 2
	s_add_u32 s38, s38, 0x100
	s_addc_u32 s39, s39, 0
	s_add_u32 s12, s12, 0x100
	s_addc_u32 s13, s13, 0
	s_cmp_gt_u32 s76, 13
	s_cbranch_scc0 .LBB0_320
	s_and_b64 vcc, exec, s[54:55]
	s_cbranch_vccz .LBB0_323
	s_barrier

; #define PG8_STAGE(bufoff, gbase, voff) do { _Pragma("unroll") for (int _i = 0; _i < 2; ++_i) \
;         __builtin_amdgcn_global_load_lds((const unsigned*)((const char*)(gbase) + (voff)[_i]), (PG8_LAS unsigned*)(lds + (bufoff) + ldsw + _i * 8192), 16, 0, 0); } while (0)
; #define PG8_LDA(dst, b, h) do { _Pragma("unroll") for (int m = 0; m < 4; ++m) _Pragma("unroll") for (int k = 0; k < 2; ++k) dst[m][k] = *(const PG8_LAS bf16x8*)(lds + PG8_SA(b, h) + aoff + m * 2048 + k * 1024); } while (0)
; #define PG8_LDB(dst, b, h) do { _Pragma("unroll") for (int n = 0; n < 2; ++n) _Pragma("unroll") for (int k = 0; k < 2; ++k) dst[n][k] = *(const PG8_LAS bf16x8*)(lds + PG8_SB(b, h) + boff + n * 2048 + k * 1024); } while (0)
; #define PG8_MMA(ai, bj, At, Bt) do { __builtin_amdgcn_s_setprio(1); _Pragma("unroll") for (int m = 0; m < 4; ++m) _Pragma("unroll") for (int n = 0; n < 2; ++n) _Pragma("unroll") for (int k = 0; k < 2; ++k) \
;         acc[ai][bj][m][n] = mma16<Epi::F16>(Bt[n][k], At[m][k], acc[ai][bj][m][n]); __builtin_amdgcn_s_setprio(0); } while (0)
; #define PG8_WAIT_V(n) asm volatile("s_waitcnt vmcnt(" #n ")" ::: "memory")
; #define PG8_WAIT_L(n) asm volatile("s_waitcnt lgkmcnt(" #n ")" ::: "memory")
; template <class Epi, class Sched, bool ALIGN_EPI = false, bool SP2 = false>
; __device__ __forceinline__ void gemm_phase(PG8_LAS unsigned char* lds, const Gemm g, const Sched& S, const Epi& E, const int wave_in) {
;     ...
;         for (int t = 0; t < nt; t += 2) {
;             const bool last = (t == nt - 2);
;             const char* a1 = cA + (size_t)(t + 1) * kstep;
;             const char* a2 = last ? nA : cA + (size_t)(t + 2) * kstep; const char* b2 = last ? nB : cB + (size_t)(t + 2) * kstep;
;             const char* a3 = a2 + kstep; const char* b3 = b2 + kstep;
;             if (last && has_next) S.a_ready(nxt);
;             if constexpr (SP2) {
;             PG8_LDB(B0, 0, 0); PG8_LDB(B1, 0, 1); PG8_SCHED; PG8_LDA(At, 0, 0); PG8_STAGE(PG8_SA(1, 1), a1 + hstep, voffA);
;             PG8_WAIT_V(8); PG8_WAIT_L(0); PG8_BAR; PG8_MMA(0, 0, At, B0); PG8_MMA(0, 1, At, B1); PG8_BAR; PG8_SCHED;
;             PG8_LDA(At, 0, 1); PG8_STAGE(PG8_SB(0, 0), b2, voffB); PG8_STAGE(PG8_SB(0, 1), b2 + hstep, voffB); PG8_STAGE(PG8_SA(0, 0), a2, voffA);
;             PG8_WAIT_V(8); PG8_WAIT_L(0); PG8_BAR; PG8_MMA(1, 0, At, B0); PG8_MMA(1, 1, At, B1); PG8_BAR; PG8_SCHED;
.LBB0_418:
	v_add_u32_e32 v58, s28, v211
	v_add_u32_e32 v78, s72, v211
	ds_read_b128 v[42:45], v58
	ds_read_b128 v[46:49], v58 offset:1024
	ds_read_b128 v[54:57], v58 offset:2048
	ds_read_b128 v[58:61], v58 offset:3072
	ds_read_b128 v[66:69], v78
	ds_read_b128 v[70:73], v78 offset:1024
	ds_read_b128 v[74:77], v78 offset:2048
	ds_read_b128 v[78:81], v78 offset:3072
	s_add_u32 s86, s62, 0x100
	s_addc_u32 s87, s63, 0
	s_cmp_eq_u32 s13, 40
	s_cselect_b32 s91, s45, s87
	s_cselect_b32 s90, s44, s86
	s_cselect_b32 s37, s61, s12
	s_cselect_b32 s36, s60, s11
	v_lshl_add_u64 v[178:179], s[62:63], 0, v[220:221]
	s_add_i32 m0, s0, 0xc000
	ds_read_b128 v[98:101], v213
	ds_read_b128 v[102:105], v213 offset:1024
	ds_read_b128 v[106:109], v213 offset:2048
	ds_read_b128 v[118:121], v213 offset:3072
	ds_read_b128 v[130:133], v213 offset:4096
	ds_read_b128 v[138:141], v213 offset:5120
	ds_read_b128 v[146:149], v213 offset:6144
	ds_read_b128 v[158:161], v213 offset:7168
	global_load_lds_dwordx4 v[178:179], off
	v_lshl_add_u64 v[178:179], s[62:63], 0, v[222:223]
	s_add_i32 m0, s0, 0xe000
	s_nop 0
	global_load_lds_dwordx4 v[178:179], off
	s_waitcnt vmcnt(8)
	s_waitcnt lgkmcnt(0)
	s_barrier
	s_setprio 1
	v_mfma_f32_16x16x32_bf16 v[190:193], v[54:57], v[98:101], v[190:193]
	v_mfma_f32_16x16x32_bf16 v[174:177], v[42:45], v[106:109], v[174:177]
	v_mfma_f32_16x16x32_bf16 v[170:173], v[54:57], v[106:109], v[170:173]
	v_mfma_f32_16x16x32_bf16 v[154:157], v[42:45], v[130:133], v[154:157]
	v_mfma_f32_16x16x32_bf16 v[150:153], v[54:57], v[130:133], v[150:153]
	v_mfma_f32_16x16x32_bf16 v[126:129], v[42:45], v[146:149], v[126:129]
	v_mfma_f32_16x16x32_bf16 v[122:125], v[54:57], v[146:149], v[122:125]
	v_mfma_f32_16x16x32_bf16 v[178:181], v[42:45], v[98:101], v[194:197]
	v_mfma_f32_16x16x32_bf16 v[190:193], v[58:61], v[102:105], v[190:193]
	v_mfma_f32_16x16x32_bf16 v[174:177], v[46:49], v[118:121], v[174:177]
	v_mfma_f32_16x16x32_bf16 v[170:173], v[58:61], v[118:121], v[170:173]
	v_mfma_f32_16x16x32_bf16 v[154:157], v[46:49], v[138:141], v[154:157]
	v_mfma_f32_16x16x32_bf16 v[150:153], v[58:61], v[138:141], v[150:153]
	v_mfma_f32_16x16x32_bf16 v[126:129], v[46:49], v[158:161], v[126:129]
	v_mfma_f32_16x16x32_bf16 v[122:125], v[58:61], v[158:161], v[122:125]
	v_mfma_f32_16x16x32_bf16 v[178:181], v[46:49], v[102:105], v[178:181]
	v_mfma_f32_16x16x32_bf16 v[186:189], v[66:69], v[98:101], v[186:189]
	v_mfma_f32_16x16x32_bf16 v[98:101], v[74:77], v[98:101], v[182:185]
	v_mfma_f32_16x16x32_bf16 v[186:189], v[70:73], v[102:105], v[186:189]
	v_mfma_f32_16x16x32_bf16 v[98:101], v[78:81], v[102:105], v[98:101]
	v_mfma_f32_16x16x32_bf16 v[102:105], v[66:69], v[106:109], v[166:169]
	v_mfma_f32_16x16x32_bf16 v[106:109], v[74:77], v[106:109], v[162:165]
	v_mfma_f32_16x16x32_bf16 v[114:117], v[66:69], v[146:149], v[114:117]
	v_mfma_f32_16x16x32_bf16 v[110:113], v[74:77], v[146:149], v[110:113]
	v_mfma_f32_16x16x32_bf16 v[102:105], v[70:73], v[118:121], v[102:105]
	v_mfma_f32_16x16x32_bf16 v[106:109], v[78:81], v[118:121], v[106:109]
	v_mfma_f32_16x16x32_bf16 v[118:121], v[66:69], v[130:133], v[142:145]
	v_mfma_f32_16x16x32_bf16 v[130:133], v[74:77], v[130:133], v[134:137]
	v_mfma_f32_16x16x32_bf16 v[114:117], v[70:73], v[158:161], v[114:117]
	v_mfma_f32_16x16x32_bf16 v[110:113], v[78:81], v[158:161], v[110:113]
	v_mfma_f32_16x16x32_bf16 v[118:121], v[70:73], v[138:141], v[118:121]
	v_mfma_f32_16x16x32_bf16 v[130:133], v[78:81], v[138:141], v[130:133]
	s_setprio 0
	s_barrier
	s_add_i32 s14, s28, s4
	v_lshl_add_u64 v[208:209], s[36:37], 0, v[0:1]
	s_mov_b32 m0, s14
	ds_read_b128 v[134:137], v213 offset:16384
	ds_read_b128 v[138:141], v213 offset:17408
	ds_read_b128 v[142:145], v213 offset:18432
	ds_read_b128 v[146:149], v213 offset:19456
	ds_read_b128 v[158:161], v213 offset:20480
	ds_read_b128 v[162:165], v213 offset:21504
	ds_read_b128 v[166:169], v213 offset:22528
	ds_read_b128 v[182:185], v213 offset:23552
	global_load_lds_dwordx4 v[208:209], off
	s_add_i32 m0, s14, 0x2000
	s_add_u32 s62, s36, 0xb0000
	v_lshl_add_u64 v[228:229], s[36:37], 0, v[218:219]
	s_addc_u32 s63, s37, 0
	s_add_i32 s14, s72, s4
	global_load_lds_dwordx4 v[228:229], off
	v_lshl_add_u64 v[194:195], s[62:63], 0, v[0:1]
	s_mov_b32 m0, s14
	v_lshl_add_u64 v[230:231], s[90:91], 0, v[214:215]
	global_load_lds_dwordx4 v[194:195], off
	v_lshl_add_u64 v[194:195], s[62:63], 0, v[218:219]
	s_add_i32 m0, s14, 0x2000
	v_lshl_add_u64 v[232:233], s[90:91], 0, v[216:217]
	global_load_lds_dwordx4 v[194:195], off
	s_mov_b32 m0, s0
	s_nop 0
	global_load_lds_dwordx4 v[230:231], off
	s_mov_b32 m0, s1
	s_nop 0
	global_load_lds_dwordx4 v[232:233], off
	s_waitcnt vmcnt(8)
	s_waitcnt lgkmcnt(0)
	s_barrier
; #define PG8_STAGE(bufoff, gbase, voff) do { _Pragma("unroll") for (int _i = 0; _i < 2; ++_i) \
;         __builtin_amdgcn_global_load_lds((const unsigned*)((const char*)(gbase) + (voff)[_i]), (PG8_LAS unsigned*)(lds + (bufoff) + ldsw + _i * 8192), 16, 0, 0); } while (0)
; #define PG8_LDA(dst, b, h) do { _Pragma("unroll") for (int m = 0; m < 4; ++m) _Pragma("unroll") for (int k = 0; k < 2; ++k) dst[m][k] = *(const PG8_LAS bf16x8*)(lds + PG8_SA(b, h) + aoff + m * 2048 + k * 1024); } while (0)
; #define PG8_LDB(dst, b, h) do { _Pragma("unroll") for (int n = 0; n < 2; ++n) _Pragma("unroll") for (int k = 0; k < 2; ++k) dst[n][k] = *(const PG8_LAS bf16x8*)(lds + PG8_SB(b, h) + boff + n * 2048 + k * 1024); } while (0)
; #define PG8_MMA(ai, bj, At, Bt) do { __builtin_amdgcn_s_setprio(1); _Pragma("unroll") for (int m = 0; m < 4; ++m) _Pragma("unroll") for (int n = 0; n < 2; ++n) _Pragma("unroll") for (int k = 0; k < 2; ++k) \
;         acc[ai][bj][m][n] = mma16<Epi::F16>(Bt[n][k], At[m][k], acc[ai][bj][m][n]); __builtin_amdgcn_s_setprio(0); } while (0)
; #define PG8_WAIT_V(n) asm volatile("s_waitcnt vmcnt(" #n ")" ::: "memory")
; #define PG8_WAIT_L(n) asm volatile("s_waitcnt lgkmcnt(" #n ")" ::: "memory")
; #define PG8_BAR __builtin_amdgcn_s_barrier()
; #define PG8_SCHED __builtin_amdgcn_sched_barrier(0)
; template <class Epi, class Sched, bool ALIGN_EPI = false, bool SP2 = false>
; __device__ __forceinline__ void gemm_phase(PG8_LAS unsigned char* lds, const Gemm g, const Sched& S, const Epi& E, const int wave_in) {
;     ...
;             PG8_WAIT_V(8); PG8_WAIT_L(0); PG8_BAR; PG8_MMA(1, 0, At, B0); PG8_MMA(1, 1, At, B1); PG8_BAR; PG8_SCHED;
;             PG8_LDB(B0, 1, 0); PG8_LDB(B1, 1, 1); PG8_SCHED; PG8_LDA(At, 1, 0); PG8_STAGE(PG8_SA(0, 1), a2 + hstep, voffA);
;             PG8_WAIT_V(8); PG8_WAIT_L(0); PG8_BAR; PG8_MMA(0, 0, At, B0); PG8_MMA(0, 1, At, B1); PG8_BAR; PG8_SCHED;
	s_setprio 1
	v_mfma_f32_16x16x32_bf16 v[94:97], v[42:45], v[134:137], v[94:97]
	v_mfma_f32_16x16x32_bf16 v[90:93], v[54:57], v[134:137], v[90:93]
	v_mfma_f32_16x16x32_bf16 v[62:65], v[42:45], v[142:145], v[62:65]
	v_mfma_f32_16x16x32_bf16 v[50:53], v[54:57], v[142:145], v[50:53]
	v_mfma_f32_16x16x32_bf16 v[30:33], v[42:45], v[158:161], v[30:33]
	v_mfma_f32_16x16x32_bf16 v[26:29], v[54:57], v[158:161], v[26:29]
	v_mfma_f32_16x16x32_bf16 v[14:17], v[42:45], v[166:169], v[14:17]
	v_mfma_f32_16x16x32_bf16 v[10:13], v[54:57], v[166:169], v[10:13]
	v_mfma_f32_16x16x32_bf16 v[94:97], v[46:49], v[138:141], v[94:97]
	v_mfma_f32_16x16x32_bf16 v[90:93], v[58:61], v[138:141], v[90:93]
	v_mfma_f32_16x16x32_bf16 v[62:65], v[46:49], v[146:149], v[62:65]
	v_mfma_f32_16x16x32_bf16 v[50:53], v[58:61], v[146:149], v[50:53]
	v_mfma_f32_16x16x32_bf16 v[30:33], v[46:49], v[162:165], v[30:33]
	v_mfma_f32_16x16x32_bf16 v[26:29], v[58:61], v[162:165], v[26:29]
	v_mfma_f32_16x16x32_bf16 v[14:17], v[46:49], v[182:185], v[14:17]
	v_mfma_f32_16x16x32_bf16 v[10:13], v[58:61], v[182:185], v[10:13]
	v_mfma_f32_16x16x32_bf16 v[38:41], v[66:69], v[142:145], v[38:41]
	v_mfma_f32_16x16x32_bf16 v[34:37], v[74:77], v[142:145], v[34:37]
	v_mfma_f32_16x16x32_bf16 v[22:25], v[66:69], v[158:161], v[22:25]
	v_mfma_f32_16x16x32_bf16 v[18:21], v[74:77], v[158:161], v[18:21]
	v_mfma_f32_16x16x32_bf16 v[6:9], v[66:69], v[166:169], v[6:9]
	v_mfma_f32_16x16x32_bf16 v[2:5], v[74:77], v[166:169], v[2:5]
	v_mfma_f32_16x16x32_bf16 v[42:45], v[66:69], v[134:137], v[86:89]
	v_mfma_f32_16x16x32_bf16 v[46:49], v[74:77], v[134:137], v[82:85]
	v_mfma_f32_16x16x32_bf16 v[38:41], v[70:73], v[146:149], v[38:41]
	v_mfma_f32_16x16x32_bf16 v[34:37], v[78:81], v[146:149], v[34:37]
	v_mfma_f32_16x16x32_bf16 v[22:25], v[70:73], v[162:165], v[22:25]
	v_mfma_f32_16x16x32_bf16 v[18:21], v[78:81], v[162:165], v[18:21]
	v_mfma_f32_16x16x32_bf16 v[6:9], v[70:73], v[182:185], v[6:9]
	v_mfma_f32_16x16x32_bf16 v[2:5], v[78:81], v[182:185], v[2:5]
	v_mfma_f32_16x16x32_bf16 v[42:45], v[70:73], v[138:141], v[42:45]
	v_mfma_f32_16x16x32_bf16 v[46:49], v[78:81], v[138:141], v[46:49]
	s_setprio 0
	s_barrier
	v_add_u32_e32 v70, s73, v211
	v_add_u32_e32 v82, s74, v211
	ds_read_b128 v[54:57], v70
	ds_read_b128 v[58:61], v70 offset:1024
	ds_read_b128 v[66:69], v70 offset:2048
	ds_read_b128 v[70:73], v70 offset:3072
	ds_read_b128 v[74:77], v82
	ds_read_b128 v[78:81], v82 offset:1024
	ds_read_b128 v[138:141], v82 offset:2048
	ds_read_b128 v[146:149], v82 offset:3072
	s_add_u32 s62, s90, 0xb0000
	s_addc_u32 s63, s91, 0
	s_mov_b32 m0, s5
	v_lshl_add_u64 v[162:163], s[62:63], 0, v[214:215]
	ds_read_b128 v[82:85], v213 offset:32768
	ds_read_b128 v[86:89], v213 offset:33792
	ds_read_b128 v[134:137], v213 offset:34816
	ds_read_b128 v[142:145], v213 offset:35840
	ds_read_b128 v[158:161], v213 offset:36864
	ds_read_b128 v[198:201], v213 offset:37888
	ds_read_b128 v[202:205], v213 offset:38912
	ds_read_b128 v[224:227], v213 offset:39936
	global_load_lds_dwordx4 v[162:163], off
	v_lshl_add_u64 v[162:163], s[62:63], 0, v[216:217]
	s_mov_b32 m0, s82
	s_nop 0
	global_load_lds_dwordx4 v[162:163], off
	s_waitcnt vmcnt(8)
	s_waitcnt lgkmcnt(0)
	s_barrier
	s_setprio 1
	v_mfma_f32_16x16x32_bf16 v[162:165], v[54:57], v[82:85], v[178:181]
	v_mfma_f32_16x16x32_bf16 v[194:197], v[58:61], v[86:89], v[162:165]
	v_mfma_f32_16x16x32_bf16 v[162:165], v[66:69], v[82:85], v[190:193]
	v_mfma_f32_16x16x32_bf16 v[190:193], v[70:73], v[86:89], v[162:165]
	v_mfma_f32_16x16x32_bf16 v[162:165], v[54:57], v[134:137], v[174:177]
	v_mfma_f32_16x16x32_bf16 v[174:177], v[58:61], v[142:145], v[162:165]
	v_mfma_f32_16x16x32_bf16 v[162:165], v[66:69], v[134:137], v[170:173]
	v_mfma_f32_16x16x32_bf16 v[154:157], v[54:57], v[158:161], v[154:157]
	v_mfma_f32_16x16x32_bf16 v[150:153], v[66:69], v[158:161], v[150:153]
	v_mfma_f32_16x16x32_bf16 v[126:129], v[54:57], v[202:205], v[126:129]
	v_mfma_f32_16x16x32_bf16 v[122:125], v[66:69], v[202:205], v[122:125]
	v_mfma_f32_16x16x32_bf16 v[170:173], v[70:73], v[142:145], v[162:165]
	v_mfma_f32_16x16x32_bf16 v[154:157], v[58:61], v[198:201], v[154:157]
	v_mfma_f32_16x16x32_bf16 v[150:153], v[70:73], v[198:201], v[150:153]
	v_mfma_f32_16x16x32_bf16 v[126:129], v[58:61], v[224:227], v[126:129]
	v_mfma_f32_16x16x32_bf16 v[122:125], v[70:73], v[224:227], v[122:125]
	v_mfma_f32_16x16x32_bf16 v[162:165], v[74:77], v[82:85], v[186:189]
	v_mfma_f32_16x16x32_bf16 v[82:85], v[138:141], v[82:85], v[98:101]
	v_mfma_f32_16x16x32_bf16 v[182:185], v[146:149], v[86:89], v[82:85]
	v_mfma_f32_16x16x32_bf16 v[82:85], v[74:77], v[134:137], v[102:105]
	v_mfma_f32_16x16x32_bf16 v[166:169], v[78:81], v[142:145], v[82:85]
	v_mfma_f32_16x16x32_bf16 v[82:85], v[138:141], v[134:137], v[106:109]
	v_mfma_f32_16x16x32_bf16 v[186:189], v[78:81], v[86:89], v[162:165]
	v_mfma_f32_16x16x32_bf16 v[162:165], v[146:149], v[142:145], v[82:85]
	v_mfma_f32_16x16x32_bf16 v[82:85], v[74:77], v[158:161], v[118:121]
	v_mfma_f32_16x16x32_bf16 v[142:145], v[78:81], v[198:201], v[82:85]
	v_mfma_f32_16x16x32_bf16 v[82:85], v[138:141], v[158:161], v[130:133]
	v_mfma_f32_16x16x32_bf16 v[134:137], v[146:149], v[198:201], v[82:85]
	v_mfma_f32_16x16x32_bf16 v[82:85], v[74:77], v[202:205], v[114:117]
	v_mfma_f32_16x16x32_bf16 v[114:117], v[78:81], v[224:227], v[82:85]
	v_mfma_f32_16x16x32_bf16 v[82:85], v[138:141], v[202:205], v[110:113]
	v_mfma_f32_16x16x32_bf16 v[110:113], v[146:149], v[224:227], v[82:85]
	s_setprio 0
	s_barrier
; #define PG8_STAGE(bufoff, gbase, voff) do { _Pragma("unroll") for (int _i = 0; _i < 2; ++_i) \
;         __builtin_amdgcn_global_load_lds((const unsigned*)((const char*)(gbase) + (voff)[_i]), (PG8_LAS unsigned*)(lds + (bufoff) + ldsw + _i * 8192), 16, 0, 0); } while (0)
; #define PG8_LDA(dst, b, h) do { _Pragma("unroll") for (int m = 0; m < 4; ++m) _Pragma("unroll") for (int k = 0; k < 2; ++k) dst[m][k] = *(const PG8_LAS bf16x8*)(lds + PG8_SA(b, h) + aoff + m * 2048 + k * 1024); } while (0)
; #define PG8_MMA(ai, bj, At, Bt) do { __builtin_amdgcn_s_setprio(1); _Pragma("unroll") for (int m = 0; m < 4; ++m) _Pragma("unroll") for (int n = 0; n < 2; ++n) _Pragma("unroll") for (int k = 0; k < 2; ++k) \
;         acc[ai][bj][m][n] = mma16<Epi::F16>(Bt[n][k], At[m][k], acc[ai][bj][m][n]); __builtin_amdgcn_s_setprio(0); } while (0)
; #define PG8_WAIT_V(n) asm volatile("s_waitcnt vmcnt(" #n ")" ::: "memory")
; #define PG8_WAIT_L(n) asm volatile("s_waitcnt lgkmcnt(" #n ")" ::: "memory")
; #define PG8_BAR __builtin_amdgcn_s_barrier()
; #define PG8_SCHED __builtin_amdgcn_sched_barrier(0)
; template <class Epi, class Sched, bool ALIGN_EPI = false, bool SP2 = false>
; __device__ __forceinline__ void gemm_phase(PG8_LAS unsigned char* lds, const Gemm g, const Sched& S, const Epi& E, const int wave_in) {
;     ...
;         for (int t = 0; t < nt; t += 2) {
;             const bool last = (t == nt - 2);
;             const char* a1 = cA + (size_t)(t + 1) * kstep;
;             const char* a2 = last ? nA : cA + (size_t)(t + 2) * kstep; const char* b2 = last ? nB : cB + (size_t)(t + 2) * kstep;
;             const char* a3 = a2 + kstep; const char* b3 = b2 + kstep;
;             if (last && has_next) S.a_ready(nxt);
;     ...
;             PG8_LDA(At, 1, 1); PG8_STAGE(PG8_SB(1, 0), b3, voffB); PG8_STAGE(PG8_SB(1, 1), b3 + hstep, voffB); PG8_STAGE(PG8_SA(1, 0), a3, voffA);
;             PG8_WAIT_V(8); PG8_WAIT_L(0); PG8_BAR; PG8_MMA(1, 0, At, B0); PG8_MMA(1, 1, At, B1); PG8_BAR; PG8_SCHED;
	s_add_i32 s14, s73, s4
	v_lshl_add_u64 v[86:87], v[208:209], 0, s[78:79]
	s_mov_b32 m0, s14
	s_nop 1
	ds_read_b128 v[82:85], v213 offset:49152
	ds_read_b128 v[98:101], v213 offset:50176
	ds_read_b128 v[102:105], v213 offset:51200
	ds_read_b128 v[106:109], v213 offset:52224
	ds_read_b128 v[118:121], v213 offset:53248
	ds_read_b128 v[130:133], v213 offset:54272
	ds_read_b128 v[158:161], v213 offset:55296
	ds_read_b128 v[178:181], v213 offset:56320
	global_load_lds_dwordx4 v[86:87], off
	s_add_i32 m0, s14, 0x2000
	s_add_u32 s36, s36, 0xb0080
	v_lshl_add_u64 v[86:87], v[228:229], 0, s[78:79]
	s_addc_u32 s37, s37, 0
	s_add_i32 s14, s74, s4
	global_load_lds_dwordx4 v[86:87], off
	v_lshl_add_u64 v[86:87], s[36:37], 0, v[0:1]
	s_mov_b32 m0, s14
	s_nop 0
	global_load_lds_dwordx4 v[86:87], off
	v_lshl_add_u64 v[86:87], s[36:37], 0, v[218:219]
	s_add_i32 m0, s14, 0x2000
	s_nop 0
	global_load_lds_dwordx4 v[86:87], off
	v_lshl_add_u64 v[86:87], v[230:231], 0, s[78:79]
	s_mov_b32 m0, s71
	s_nop 0
	global_load_lds_dwordx4 v[86:87], off
	v_lshl_add_u64 v[86:87], v[232:233], 0, s[78:79]
	s_mov_b32 m0, s6
	s_nop 0
	global_load_lds_dwordx4 v[86:87], off
	s_waitcnt vmcnt(8)
	s_waitcnt lgkmcnt(0)
	s_barrier
	s_setprio 1
	v_mfma_f32_16x16x32_bf16 v[86:89], v[54:57], v[82:85], v[94:97]
	v_mfma_f32_16x16x32_bf16 v[94:97], v[58:61], v[98:101], v[86:89]
	v_mfma_f32_16x16x32_bf16 v[86:89], v[66:69], v[82:85], v[90:93]
	v_mfma_f32_16x16x32_bf16 v[62:65], v[54:57], v[102:105], v[62:65]
	v_mfma_f32_16x16x32_bf16 v[50:53], v[66:69], v[102:105], v[50:53]
	v_mfma_f32_16x16x32_bf16 v[30:33], v[54:57], v[118:121], v[30:33]
	v_mfma_f32_16x16x32_bf16 v[26:29], v[66:69], v[118:121], v[26:29]
	v_mfma_f32_16x16x32_bf16 v[14:17], v[54:57], v[158:161], v[14:17]
	v_mfma_f32_16x16x32_bf16 v[10:13], v[66:69], v[158:161], v[10:13]
	v_mfma_f32_16x16x32_bf16 v[90:93], v[70:73], v[98:101], v[86:89]
	v_mfma_f32_16x16x32_bf16 v[62:65], v[58:61], v[106:109], v[62:65]
	v_mfma_f32_16x16x32_bf16 v[50:53], v[70:73], v[106:109], v[50:53]
	v_mfma_f32_16x16x32_bf16 v[30:33], v[58:61], v[130:133], v[30:33]
	v_mfma_f32_16x16x32_bf16 v[26:29], v[70:73], v[130:133], v[26:29]
	v_mfma_f32_16x16x32_bf16 v[14:17], v[58:61], v[178:181], v[14:17]
	v_mfma_f32_16x16x32_bf16 v[10:13], v[70:73], v[178:181], v[10:13]
	v_mfma_f32_16x16x32_bf16 v[42:45], v[74:77], v[82:85], v[42:45]
	v_mfma_f32_16x16x32_bf16 v[86:89], v[78:81], v[98:101], v[42:45]
	v_mfma_f32_16x16x32_bf16 v[42:45], v[138:141], v[82:85], v[46:49]
	v_mfma_f32_16x16x32_bf16 v[38:41], v[74:77], v[102:105], v[38:41]
	v_mfma_f32_16x16x32_bf16 v[34:37], v[138:141], v[102:105], v[34:37]
	v_mfma_f32_16x16x32_bf16 v[22:25], v[74:77], v[118:121], v[22:25]
	v_mfma_f32_16x16x32_bf16 v[18:21], v[138:141], v[118:121], v[18:21]
	v_mfma_f32_16x16x32_bf16 v[6:9], v[74:77], v[158:161], v[6:9]
	v_mfma_f32_16x16x32_bf16 v[2:5], v[138:141], v[158:161], v[2:5]
	v_mfma_f32_16x16x32_bf16 v[82:85], v[146:149], v[98:101], v[42:45]
	v_mfma_f32_16x16x32_bf16 v[38:41], v[78:81], v[106:109], v[38:41]
	v_mfma_f32_16x16x32_bf16 v[34:37], v[146:149], v[106:109], v[34:37]
	v_mfma_f32_16x16x32_bf16 v[22:25], v[78:81], v[130:133], v[22:25]
	v_mfma_f32_16x16x32_bf16 v[18:21], v[146:149], v[130:133], v[18:21]
	v_mfma_f32_16x16x32_bf16 v[6:9], v[78:81], v[178:181], v[6:9]
	v_mfma_f32_16x16x32_bf16 v[2:5], v[146:149], v[178:181], v[2:5]
	s_setprio 0
	s_barrier
	s_add_i32 s13, s13, 2
	s_add_u32 s11, s11, 0x100
	s_addc_u32 s12, s12, 0
	s_cmp_gt_u32 s13, 41
	s_mov_b64 s[62:63], s[86:87]
	s_cbranch_scc0 .LBB0_418
	s_and_b64 vcc, exec, s[58:59]
	s_cbranch_vccz .LBB0_421
	s_barrier

; #define PG8_STAGE(bufoff, gbase, voff) do { _Pragma("unroll") for (int _i = 0; _i < 2; ++_i) \
;         __builtin_amdgcn_global_load_lds((const unsigned*)((const char*)(gbase) + (voff)[_i]), (PG8_LAS unsigned*)(lds + (bufoff) + ldsw + _i * 8192), 16, 0, 0); } while (0)
; #define PG8_LDA(dst, b, h) do { _Pragma("unroll") for (int m = 0; m < 4; ++m) _Pragma("unroll") for (int k = 0; k < 2; ++k) dst[m][k] = *(const PG8_LAS bf16x8*)(lds + PG8_SA(b, h) + aoff + m * 2048 + k * 1024); } while (0)
; #define PG8_LDB(dst, b, h) do { _Pragma("unroll") for (int n = 0; n < 2; ++n) _Pragma("unroll") for (int k = 0; k < 2; ++k) dst[n][k] = *(const PG8_LAS bf16x8*)(lds + PG8_SB(b, h) + boff + n * 2048 + k * 1024); } while (0)
; #define PG8_MMA(ai, bj, At, Bt) do { __builtin_amdgcn_s_setprio(1); _Pragma("unroll") for (int m = 0; m < 4; ++m) _Pragma("unroll") for (int n = 0; n < 2; ++n) _Pragma("unroll") for (int k = 0; k < 2; ++k) \
;         acc[ai][bj][m][n] = mma16<Epi::F16>(Bt[n][k], At[m][k], acc[ai][bj][m][n]); __builtin_amdgcn_s_setprio(0); } while (0)
; #define PG8_WAIT_V(n) asm volatile("s_waitcnt vmcnt(" #n ")" ::: "memory")
; #define PG8_WAIT_L(n) asm volatile("s_waitcnt lgkmcnt(" #n ")" ::: "memory")
; template <class Epi, class Sched, bool ALIGN_EPI = false, bool SP2 = false>
; __device__ __forceinline__ void gemm_phase(PG8_LAS unsigned char* lds, const Gemm g, const Sched& S, const Epi& E, const int wave_in) {
;     ...
;         for (int t = 0; t < nt; t += 2) {
;             const bool last = (t == nt - 2);
;             const char* a1 = cA + (size_t)(t + 1) * kstep;
;             const char* a2 = last ? nA : cA + (size_t)(t + 2) * kstep; const char* b2 = last ? nB : cB + (size_t)(t + 2) * kstep;
;             const char* a3 = a2 + kstep; const char* b3 = b2 + kstep;
;             if (last && has_next) S.a_ready(nxt);
;             if constexpr (SP2) {
;             PG8_LDB(B0, 0, 0); PG8_LDB(B1, 0, 1); PG8_SCHED; PG8_LDA(At, 0, 0); PG8_STAGE(PG8_SA(1, 1), a1 + hstep, voffA);
;             PG8_WAIT_V(8); PG8_WAIT_L(0); PG8_BAR; PG8_MMA(0, 0, At, B0); PG8_MMA(0, 1, At, B1); PG8_BAR; PG8_SCHED;
;             PG8_LDA(At, 0, 1); PG8_STAGE(PG8_SB(0, 0), b2, voffB); PG8_STAGE(PG8_SB(0, 1), b2 + hstep, voffB); PG8_STAGE(PG8_SA(0, 0), a2, voffA);
;             PG8_WAIT_V(8); PG8_WAIT_L(0); PG8_BAR; PG8_MMA(1, 0, At, B0); PG8_MMA(1, 1, At, B1); PG8_BAR; PG8_SCHED;
.LBB0_594:
	v_add_u32_e32 v58, s28, v210
	v_add_u32_e32 v86, s72, v210
	ds_read_b128 v[42:45], v58
	ds_read_b128 v[46:49], v58 offset:1024
	ds_read_b128 v[54:57], v58 offset:2048
	ds_read_b128 v[58:61], v58 offset:3072
	ds_read_b128 v[74:77], v86
	ds_read_b128 v[78:81], v86 offset:1024
	ds_read_b128 v[82:85], v86 offset:2048
	ds_read_b128 v[86:89], v86 offset:3072
	s_add_u32 s13, s38, 0xfffc0080
	s_addc_u32 s14, s39, -1
	s_cmp_eq_u32 s12, 12
	s_cselect_b32 s43, s9, s14
	s_cselect_b32 s42, s10, s13
	s_cselect_b32 s37, s11, s59
	s_cselect_b32 s36, s44, s45
	v_lshl_add_u64 v[212:213], s[38:39], 0, v[186:187]
	s_add_i32 m0, s83, 0xc000
	ds_read_b128 v[162:165], v229
	ds_read_b128 v[166:169], v229 offset:1024
	ds_read_b128 v[170:173], v229 offset:2048
	ds_read_b128 v[174:177], v229 offset:3072
	ds_read_b128 v[190:193], v229 offset:4096
	ds_read_b128 v[194:197], v229 offset:5120
	ds_read_b128 v[198:201], v229 offset:6144
	ds_read_b128 v[202:205], v229 offset:7168
	global_load_lds_dwordx4 v[212:213], off
	v_lshl_add_u64 v[212:213], s[38:39], 0, v[188:189]
	s_add_i32 m0, s83, 0xe000
	s_nop 0
	global_load_lds_dwordx4 v[212:213], off
	s_waitcnt vmcnt(8)
	s_waitcnt lgkmcnt(0)
	s_barrier
	s_setprio 1
	v_mfma_f32_16x16x32_f16 v[158:161], v[42:45], v[162:165], v[158:161]
	v_mfma_f32_16x16x32_f16 v[154:157], v[54:57], v[162:165], v[154:157]
	v_mfma_f32_16x16x32_f16 v[142:145], v[42:45], v[170:173], v[142:145]
	v_mfma_f32_16x16x32_f16 v[138:141], v[54:57], v[170:173], v[138:141]
	v_mfma_f32_16x16x32_f16 v[126:129], v[42:45], v[190:193], v[126:129]
	v_mfma_f32_16x16x32_f16 v[122:125], v[54:57], v[190:193], v[122:125]
	v_mfma_f32_16x16x32_f16 v[110:113], v[42:45], v[198:201], v[110:113]
	v_mfma_f32_16x16x32_f16 v[106:109], v[54:57], v[198:201], v[106:109]
	v_mfma_f32_16x16x32_f16 v[158:161], v[46:49], v[166:169], v[158:161]
	v_mfma_f32_16x16x32_f16 v[154:157], v[58:61], v[166:169], v[154:157]
	v_mfma_f32_16x16x32_f16 v[142:145], v[46:49], v[174:177], v[142:145]
	v_mfma_f32_16x16x32_f16 v[138:141], v[58:61], v[174:177], v[138:141]
	v_mfma_f32_16x16x32_f16 v[126:129], v[46:49], v[194:197], v[126:129]
	v_mfma_f32_16x16x32_f16 v[122:125], v[58:61], v[194:197], v[122:125]
	v_mfma_f32_16x16x32_f16 v[110:113], v[46:49], v[202:205], v[110:113]
	v_mfma_f32_16x16x32_f16 v[106:109], v[58:61], v[202:205], v[106:109]
	v_mfma_f32_16x16x32_f16 v[150:153], v[74:77], v[162:165], v[150:153]
	v_mfma_f32_16x16x32_f16 v[146:149], v[82:85], v[162:165], v[146:149]
	v_mfma_f32_16x16x32_f16 v[134:137], v[74:77], v[170:173], v[134:137]
	v_mfma_f32_16x16x32_f16 v[130:133], v[82:85], v[170:173], v[130:133]
	v_mfma_f32_16x16x32_f16 v[118:121], v[74:77], v[190:193], v[118:121]
	v_mfma_f32_16x16x32_f16 v[114:117], v[82:85], v[190:193], v[114:117]
	v_mfma_f32_16x16x32_f16 v[102:105], v[74:77], v[198:201], v[102:105]
	v_mfma_f32_16x16x32_f16 v[98:101], v[82:85], v[198:201], v[98:101]
	v_mfma_f32_16x16x32_f16 v[150:153], v[78:81], v[166:169], v[150:153]
	v_mfma_f32_16x16x32_f16 v[146:149], v[86:89], v[166:169], v[146:149]
	v_mfma_f32_16x16x32_f16 v[134:137], v[78:81], v[174:177], v[134:137]
	v_mfma_f32_16x16x32_f16 v[130:133], v[86:89], v[174:177], v[130:133]
	v_mfma_f32_16x16x32_f16 v[118:121], v[78:81], v[194:197], v[118:121]
	v_mfma_f32_16x16x32_f16 v[114:117], v[86:89], v[194:197], v[114:117]
	v_mfma_f32_16x16x32_f16 v[102:105], v[78:81], v[202:205], v[102:105]
	v_mfma_f32_16x16x32_f16 v[98:101], v[86:89], v[202:205], v[98:101]
	s_setprio 0
	s_barrier
	s_add_i32 s13, s28, s82
	v_lshl_add_u64 v[212:213], s[36:37], 0, v[0:1]
	s_mov_b32 m0, s13
	ds_read_b128 v[162:165], v229 offset:16384
	ds_read_b128 v[166:169], v229 offset:17408
	ds_read_b128 v[170:173], v229 offset:18432
	ds_read_b128 v[174:177], v229 offset:19456
	ds_read_b128 v[190:193], v229 offset:20480
	ds_read_b128 v[194:197], v229 offset:21504
	ds_read_b128 v[198:201], v229 offset:22528
	ds_read_b128 v[202:205], v229 offset:23552
	global_load_lds_dwordx4 v[212:213], off
	s_add_i32 m0, s13, 0x2000
	s_add_u32 vcc_lo, s36, 0x40000
	v_lshl_add_u64 v[214:215], s[36:37], 0, v[182:183]
	s_addc_u32 vcc_hi, s37, 0
	s_add_i32 s13, s72, s82
	global_load_lds_dwordx4 v[214:215], off
	v_lshl_add_u64 v[216:217], vcc, 0, v[0:1]
	s_mov_b32 m0, s13
	v_lshl_add_u64 v[218:219], s[42:43], 0, v[180:181]
	global_load_lds_dwordx4 v[216:217], off
	v_lshl_add_u64 v[216:217], vcc, 0, v[182:183]
	s_add_i32 m0, s13, 0x2000
	s_nop 0
	global_load_lds_dwordx4 v[216:217], off
	v_lshl_add_u64 v[216:217], s[42:43], 0, v[178:179]
	s_mov_b32 m0, s83
	s_nop 0
	global_load_lds_dwordx4 v[216:217], off
	s_mov_b32 m0, s4
	s_nop 0
	global_load_lds_dwordx4 v[218:219], off
	s_waitcnt vmcnt(8)
	s_waitcnt lgkmcnt(0)
	s_barrier
; #define PG8_STAGE(bufoff, gbase, voff) do { _Pragma("unroll") for (int _i = 0; _i < 2; ++_i) \
;         __builtin_amdgcn_global_load_lds((const unsigned*)((const char*)(gbase) + (voff)[_i]), (PG8_LAS unsigned*)(lds + (bufoff) + ldsw + _i * 8192), 16, 0, 0); } while (0)
; #define PG8_LDA(dst, b, h) do { _Pragma("unroll") for (int m = 0; m < 4; ++m) _Pragma("unroll") for (int k = 0; k < 2; ++k) dst[m][k] = *(const PG8_LAS bf16x8*)(lds + PG8_SA(b, h) + aoff + m * 2048 + k * 1024); } while (0)
; #define PG8_LDB(dst, b, h) do { _Pragma("unroll") for (int n = 0; n < 2; ++n) _Pragma("unroll") for (int k = 0; k < 2; ++k) dst[n][k] = *(const PG8_LAS bf16x8*)(lds + PG8_SB(b, h) + boff + n * 2048 + k * 1024); } while (0)
; #define PG8_MMA(ai, bj, At, Bt) do { __builtin_amdgcn_s_setprio(1); _Pragma("unroll") for (int m = 0; m < 4; ++m) _Pragma("unroll") for (int n = 0; n < 2; ++n) _Pragma("unroll") for (int k = 0; k < 2; ++k) \
;         acc[ai][bj][m][n] = mma16<Epi::F16>(Bt[n][k], At[m][k], acc[ai][bj][m][n]); __builtin_amdgcn_s_setprio(0); } while (0)
; #define PG8_WAIT_V(n) asm volatile("s_waitcnt vmcnt(" #n ")" ::: "memory")
; #define PG8_WAIT_L(n) asm volatile("s_waitcnt lgkmcnt(" #n ")" ::: "memory")
; #define PG8_BAR __builtin_amdgcn_s_barrier()
; #define PG8_SCHED __builtin_amdgcn_sched_barrier(0)
; template <class Epi, class Sched, bool ALIGN_EPI = false, bool SP2 = false>
; __device__ __forceinline__ void gemm_phase(PG8_LAS unsigned char* lds, const Gemm g, const Sched& S, const Epi& E, const int wave_in) {
;     ...
;             PG8_WAIT_V(8); PG8_WAIT_L(0); PG8_BAR; PG8_MMA(1, 0, At, B0); PG8_MMA(1, 1, At, B1); PG8_BAR; PG8_SCHED;
;             PG8_LDB(B0, 1, 0); PG8_LDB(B1, 1, 1); PG8_SCHED; PG8_LDA(At, 1, 0); PG8_STAGE(PG8_SA(0, 1), a2 + hstep, voffA);
;             PG8_WAIT_V(8); PG8_WAIT_L(0); PG8_BAR; PG8_MMA(0, 0, At, B0); PG8_MMA(0, 1, At, B1); PG8_BAR; PG8_SCHED;
	s_setprio 1
	v_mfma_f32_16x16x32_f16 v[94:97], v[42:45], v[162:165], v[94:97]
	v_mfma_f32_16x16x32_f16 v[90:93], v[54:57], v[162:165], v[90:93]
	v_mfma_f32_16x16x32_f16 v[62:65], v[42:45], v[170:173], v[62:65]
	v_mfma_f32_16x16x32_f16 v[50:53], v[54:57], v[170:173], v[50:53]
	v_mfma_f32_16x16x32_f16 v[30:33], v[42:45], v[190:193], v[30:33]
	v_mfma_f32_16x16x32_f16 v[26:29], v[54:57], v[190:193], v[26:29]
	v_mfma_f32_16x16x32_f16 v[14:17], v[42:45], v[198:201], v[14:17]
	v_mfma_f32_16x16x32_f16 v[10:13], v[54:57], v[198:201], v[10:13]
	v_mfma_f32_16x16x32_f16 v[94:97], v[46:49], v[166:169], v[94:97]
	v_mfma_f32_16x16x32_f16 v[90:93], v[58:61], v[166:169], v[90:93]
	v_mfma_f32_16x16x32_f16 v[62:65], v[46:49], v[174:177], v[62:65]
	v_mfma_f32_16x16x32_f16 v[50:53], v[58:61], v[174:177], v[50:53]
	v_mfma_f32_16x16x32_f16 v[30:33], v[46:49], v[194:197], v[30:33]
	v_mfma_f32_16x16x32_f16 v[26:29], v[58:61], v[194:197], v[26:29]
	v_mfma_f32_16x16x32_f16 v[14:17], v[46:49], v[202:205], v[14:17]
	v_mfma_f32_16x16x32_f16 v[10:13], v[58:61], v[202:205], v[10:13]
	v_mfma_f32_16x16x32_f16 v[38:41], v[74:77], v[170:173], v[38:41]
	v_mfma_f32_16x16x32_f16 v[34:37], v[82:85], v[170:173], v[34:37]
	v_mfma_f32_16x16x32_f16 v[22:25], v[74:77], v[190:193], v[22:25]
	v_mfma_f32_16x16x32_f16 v[18:21], v[82:85], v[190:193], v[18:21]
	v_mfma_f32_16x16x32_f16 v[6:9], v[74:77], v[198:201], v[6:9]
	v_mfma_f32_16x16x32_f16 v[2:5], v[82:85], v[198:201], v[2:5]
	v_mfma_f32_16x16x32_f16 v[42:45], v[74:77], v[162:165], v[70:73]
	v_mfma_f32_16x16x32_f16 v[46:49], v[82:85], v[162:165], v[66:69]
	v_mfma_f32_16x16x32_f16 v[38:41], v[78:81], v[174:177], v[38:41]
	v_mfma_f32_16x16x32_f16 v[34:37], v[86:89], v[174:177], v[34:37]
	v_mfma_f32_16x16x32_f16 v[22:25], v[78:81], v[194:197], v[22:25]
	v_mfma_f32_16x16x32_f16 v[18:21], v[86:89], v[194:197], v[18:21]
	v_mfma_f32_16x16x32_f16 v[6:9], v[78:81], v[202:205], v[6:9]
	v_mfma_f32_16x16x32_f16 v[2:5], v[86:89], v[202:205], v[2:5]
	v_mfma_f32_16x16x32_f16 v[42:45], v[78:81], v[166:169], v[42:45]
	v_mfma_f32_16x16x32_f16 v[46:49], v[86:89], v[166:169], v[46:49]
	s_setprio 0
	s_barrier
	v_add_u32_e32 v70, s73, v210
	v_add_u32_e32 v86, s74, v210
	ds_read_b128 v[54:57], v70
	ds_read_b128 v[58:61], v70 offset:1024
	ds_read_b128 v[66:69], v70 offset:2048
	ds_read_b128 v[70:73], v70 offset:3072
	ds_read_b128 v[74:77], v86
	ds_read_b128 v[78:81], v86 offset:1024
	ds_read_b128 v[82:85], v86 offset:2048
	ds_read_b128 v[86:89], v86 offset:3072
	s_add_u32 s42, s42, 0x40000
	s_addc_u32 s43, s43, 0
	s_mov_b32 m0, s5
	v_lshl_add_u64 v[220:221], s[42:43], 0, v[178:179]
	ds_read_b128 v[162:165], v229 offset:32768
	ds_read_b128 v[166:169], v229 offset:33792
	ds_read_b128 v[170:173], v229 offset:34816
	ds_read_b128 v[174:177], v229 offset:35840
	ds_read_b128 v[190:193], v229 offset:36864
	ds_read_b128 v[194:197], v229 offset:37888
	ds_read_b128 v[198:201], v229 offset:38912
	ds_read_b128 v[202:205], v229 offset:39936
	global_load_lds_dwordx4 v[220:221], off
	v_lshl_add_u64 v[220:221], s[42:43], 0, v[180:181]
	s_mov_b32 m0, s0
	s_nop 0
	global_load_lds_dwordx4 v[220:221], off
	s_waitcnt vmcnt(8)
	s_waitcnt lgkmcnt(0)
	s_barrier
	s_setprio 1
	v_mfma_f32_16x16x32_f16 v[158:161], v[54:57], v[162:165], v[158:161]
	v_mfma_f32_16x16x32_f16 v[154:157], v[66:69], v[162:165], v[154:157]
	v_mfma_f32_16x16x32_f16 v[142:145], v[54:57], v[170:173], v[142:145]
	v_mfma_f32_16x16x32_f16 v[138:141], v[66:69], v[170:173], v[138:141]
	v_mfma_f32_16x16x32_f16 v[126:129], v[54:57], v[190:193], v[126:129]
	v_mfma_f32_16x16x32_f16 v[122:125], v[66:69], v[190:193], v[122:125]
	v_mfma_f32_16x16x32_f16 v[110:113], v[54:57], v[198:201], v[110:113]
	v_mfma_f32_16x16x32_f16 v[106:109], v[66:69], v[198:201], v[106:109]
	v_mfma_f32_16x16x32_f16 v[158:161], v[58:61], v[166:169], v[158:161]
	v_mfma_f32_16x16x32_f16 v[154:157], v[70:73], v[166:169], v[154:157]
	v_mfma_f32_16x16x32_f16 v[142:145], v[58:61], v[174:177], v[142:145]
	v_mfma_f32_16x16x32_f16 v[138:141], v[70:73], v[174:177], v[138:141]
	v_mfma_f32_16x16x32_f16 v[126:129], v[58:61], v[194:197], v[126:129]
	v_mfma_f32_16x16x32_f16 v[122:125], v[70:73], v[194:197], v[122:125]
	v_mfma_f32_16x16x32_f16 v[110:113], v[58:61], v[202:205], v[110:113]
	v_mfma_f32_16x16x32_f16 v[106:109], v[70:73], v[202:205], v[106:109]
	v_mfma_f32_16x16x32_f16 v[150:153], v[74:77], v[162:165], v[150:153]
	v_mfma_f32_16x16x32_f16 v[146:149], v[82:85], v[162:165], v[146:149]
	v_mfma_f32_16x16x32_f16 v[134:137], v[74:77], v[170:173], v[134:137]
	v_mfma_f32_16x16x32_f16 v[130:133], v[82:85], v[170:173], v[130:133]
	v_mfma_f32_16x16x32_f16 v[118:121], v[74:77], v[190:193], v[118:121]
	v_mfma_f32_16x16x32_f16 v[114:117], v[82:85], v[190:193], v[114:117]
	v_mfma_f32_16x16x32_f16 v[102:105], v[74:77], v[198:201], v[102:105]
	v_mfma_f32_16x16x32_f16 v[98:101], v[82:85], v[198:201], v[98:101]
	v_mfma_f32_16x16x32_f16 v[150:153], v[78:81], v[166:169], v[150:153]
	v_mfma_f32_16x16x32_f16 v[146:149], v[86:89], v[166:169], v[146:149]
	v_mfma_f32_16x16x32_f16 v[134:137], v[78:81], v[174:177], v[134:137]
	v_mfma_f32_16x16x32_f16 v[130:133], v[86:89], v[174:177], v[130:133]
	v_mfma_f32_16x16x32_f16 v[118:121], v[78:81], v[194:197], v[118:121]
	v_mfma_f32_16x16x32_f16 v[114:117], v[86:89], v[194:197], v[114:117]
	v_mfma_f32_16x16x32_f16 v[102:105], v[78:81], v[202:205], v[102:105]
	v_mfma_f32_16x16x32_f16 v[98:101], v[86:89], v[202:205], v[98:101]
	s_setprio 0
	s_barrier
; #define PG8_STAGE(bufoff, gbase, voff) do { _Pragma("unroll") for (int _i = 0; _i < 2; ++_i) \
;         __builtin_amdgcn_global_load_lds((const unsigned*)((const char*)(gbase) + (voff)[_i]), (PG8_LAS unsigned*)(lds + (bufoff) + ldsw + _i * 8192), 16, 0, 0); } while (0)
; #define PG8_LDA(dst, b, h) do { _Pragma("unroll") for (int m = 0; m < 4; ++m) _Pragma("unroll") for (int k = 0; k < 2; ++k) dst[m][k] = *(const PG8_LAS bf16x8*)(lds + PG8_SA(b, h) + aoff + m * 2048 + k * 1024); } while (0)
; #define PG8_MMA(ai, bj, At, Bt) do { __builtin_amdgcn_s_setprio(1); _Pragma("unroll") for (int m = 0; m < 4; ++m) _Pragma("unroll") for (int n = 0; n < 2; ++n) _Pragma("unroll") for (int k = 0; k < 2; ++k) \
;         acc[ai][bj][m][n] = mma16<Epi::F16>(Bt[n][k], At[m][k], acc[ai][bj][m][n]); __builtin_amdgcn_s_setprio(0); } while (0)
; #define PG8_WAIT_V(n) asm volatile("s_waitcnt vmcnt(" #n ")" ::: "memory")
; #define PG8_WAIT_L(n) asm volatile("s_waitcnt lgkmcnt(" #n ")" ::: "memory")
; #define PG8_BAR __builtin_amdgcn_s_barrier()
; #define PG8_SCHED __builtin_amdgcn_sched_barrier(0)
; template <class Epi, class Sched, bool ALIGN_EPI = false, bool SP2 = false>
; __device__ __forceinline__ void gemm_phase(PG8_LAS unsigned char* lds, const Gemm g, const Sched& S, const Epi& E, const int wave_in) {
;     ...
;         for (int t = 0; t < nt; t += 2) {
;             const bool last = (t == nt - 2);
;             const char* a1 = cA + (size_t)(t + 1) * kstep;
;             const char* a2 = last ? nA : cA + (size_t)(t + 2) * kstep; const char* b2 = last ? nB : cB + (size_t)(t + 2) * kstep;
;             const char* a3 = a2 + kstep; const char* b3 = b2 + kstep;
;             if (last && has_next) S.a_ready(nxt);
;     ...
;             PG8_LDA(At, 1, 1); PG8_STAGE(PG8_SB(1, 0), b3, voffB); PG8_STAGE(PG8_SB(1, 1), b3 + hstep, voffB); PG8_STAGE(PG8_SA(1, 0), a3, voffA);
;             PG8_WAIT_V(8); PG8_WAIT_L(0); PG8_BAR; PG8_MMA(1, 0, At, B0); PG8_MMA(1, 1, At, B1); PG8_BAR; PG8_SCHED;
	s_add_i32 s13, s73, s82
	v_lshl_add_u64 v[212:213], v[212:213], 0, s[78:79]
	s_mov_b32 m0, s13
	ds_read_b128 v[162:165], v229 offset:49152
	ds_read_b128 v[166:169], v229 offset:50176
	ds_read_b128 v[170:173], v229 offset:51200
	ds_read_b128 v[174:177], v229 offset:52224
	ds_read_b128 v[190:193], v229 offset:53248
	ds_read_b128 v[194:197], v229 offset:54272
	ds_read_b128 v[198:201], v229 offset:55296
	ds_read_b128 v[202:205], v229 offset:56320
	global_load_lds_dwordx4 v[212:213], off
	s_add_i32 m0, s13, 0x2000
	s_add_u32 s36, s36, 0x40080
	v_lshl_add_u64 v[212:213], v[214:215], 0, s[78:79]
	s_addc_u32 s37, s37, 0
	s_add_i32 s13, s74, s82
	global_load_lds_dwordx4 v[212:213], off
	v_lshl_add_u64 v[212:213], s[36:37], 0, v[0:1]
	s_mov_b32 m0, s13
	s_nop 0
	global_load_lds_dwordx4 v[212:213], off
	v_lshl_add_u64 v[212:213], s[36:37], 0, v[182:183]
	s_add_i32 m0, s13, 0x2000
	s_nop 0
	global_load_lds_dwordx4 v[212:213], off
	v_lshl_add_u64 v[212:213], v[216:217], 0, s[78:79]
	s_mov_b32 m0, s1
	s_nop 0
	global_load_lds_dwordx4 v[212:213], off
	v_lshl_add_u64 v[212:213], v[218:219], 0, s[78:79]
	s_mov_b32 m0, s76
	s_nop 0
	global_load_lds_dwordx4 v[212:213], off
	s_waitcnt vmcnt(8)
	s_waitcnt lgkmcnt(0)
	s_barrier
	s_setprio 1
	v_mfma_f32_16x16x32_f16 v[94:97], v[54:57], v[162:165], v[94:97]
	v_mfma_f32_16x16x32_f16 v[90:93], v[66:69], v[162:165], v[90:93]
	v_mfma_f32_16x16x32_f16 v[62:65], v[54:57], v[170:173], v[62:65]
	v_mfma_f32_16x16x32_f16 v[50:53], v[66:69], v[170:173], v[50:53]
	v_mfma_f32_16x16x32_f16 v[30:33], v[54:57], v[190:193], v[30:33]
	v_mfma_f32_16x16x32_f16 v[26:29], v[66:69], v[190:193], v[26:29]
	v_mfma_f32_16x16x32_f16 v[14:17], v[54:57], v[198:201], v[14:17]
	v_mfma_f32_16x16x32_f16 v[10:13], v[66:69], v[198:201], v[10:13]
	v_mfma_f32_16x16x32_f16 v[94:97], v[58:61], v[166:169], v[94:97]
	v_mfma_f32_16x16x32_f16 v[90:93], v[70:73], v[166:169], v[90:93]
	v_mfma_f32_16x16x32_f16 v[62:65], v[58:61], v[174:177], v[62:65]
	v_mfma_f32_16x16x32_f16 v[50:53], v[70:73], v[174:177], v[50:53]
	v_mfma_f32_16x16x32_f16 v[30:33], v[58:61], v[194:197], v[30:33]
	v_mfma_f32_16x16x32_f16 v[26:29], v[70:73], v[194:197], v[26:29]
	v_mfma_f32_16x16x32_f16 v[14:17], v[58:61], v[202:205], v[14:17]
	v_mfma_f32_16x16x32_f16 v[10:13], v[70:73], v[202:205], v[10:13]
	v_mfma_f32_16x16x32_f16 v[42:45], v[74:77], v[162:165], v[42:45]
	v_mfma_f32_16x16x32_f16 v[70:73], v[78:81], v[166:169], v[42:45]
	v_mfma_f32_16x16x32_f16 v[42:45], v[82:85], v[162:165], v[46:49]
	v_mfma_f32_16x16x32_f16 v[38:41], v[74:77], v[170:173], v[38:41]
	v_mfma_f32_16x16x32_f16 v[34:37], v[82:85], v[170:173], v[34:37]
	v_mfma_f32_16x16x32_f16 v[22:25], v[74:77], v[190:193], v[22:25]
	v_mfma_f32_16x16x32_f16 v[18:21], v[82:85], v[190:193], v[18:21]
	v_mfma_f32_16x16x32_f16 v[6:9], v[74:77], v[198:201], v[6:9]
	v_mfma_f32_16x16x32_f16 v[2:5], v[82:85], v[198:201], v[2:5]
	v_mfma_f32_16x16x32_f16 v[66:69], v[86:89], v[166:169], v[42:45]
	v_mfma_f32_16x16x32_f16 v[38:41], v[78:81], v[174:177], v[38:41]
	v_mfma_f32_16x16x32_f16 v[34:37], v[86:89], v[174:177], v[34:37]
	v_mfma_f32_16x16x32_f16 v[22:25], v[78:81], v[194:197], v[22:25]
	v_mfma_f32_16x16x32_f16 v[18:21], v[86:89], v[194:197], v[18:21]
	v_mfma_f32_16x16x32_f16 v[6:9], v[78:81], v[202:205], v[6:9]
	v_mfma_f32_16x16x32_f16 v[2:5], v[86:89], v[202:205], v[2:5]
	s_setprio 0
	s_barrier
	s_add_i32 s12, s12, 2
	s_add_u32 s38, s38, 0x100
	s_addc_u32 s39, s39, 0
	s_add_u32 s45, s45, 0x100
	s_addc_u32 s59, s59, 0
	s_cmp_gt_u32 s12, 13
	s_cbranch_scc0 .LBB0_594
	s_and_b64 vcc, exec, s[56:57]
	s_cbranch_vccz .LBB0_597
	s_barrier

; #define PG8_STAGE(bufoff, gbase, voff) do { _Pragma("unroll") for (int _i = 0; _i < 2; ++_i) \
;         __builtin_amdgcn_global_load_lds((const unsigned*)((const char*)(gbase) + (voff)[_i]), (PG8_LAS unsigned*)(lds + (bufoff) + ldsw + _i * 8192), 16, 0, 0); } while (0)
; #define PG8_LDA(dst, b, h) do { _Pragma("unroll") for (int m = 0; m < 4; ++m) _Pragma("unroll") for (int k = 0; k < 2; ++k) dst[m][k] = *(const PG8_LAS bf16x8*)(lds + PG8_SA(b, h) + aoff + m * 2048 + k * 1024); } while (0)
; #define PG8_LDB(dst, b, h) do { _Pragma("unroll") for (int n = 0; n < 2; ++n) _Pragma("unroll") for (int k = 0; k < 2; ++k) dst[n][k] = *(const PG8_LAS bf16x8*)(lds + PG8_SB(b, h) + boff + n * 2048 + k * 1024); } while (0)
; #define PG8_MMA(ai, bj, At, Bt) do { __builtin_amdgcn_s_setprio(1); _Pragma("unroll") for (int m = 0; m < 4; ++m) _Pragma("unroll") for (int n = 0; n < 2; ++n) _Pragma("unroll") for (int k = 0; k < 2; ++k) \
;         acc[ai][bj][m][n] = mma16<Epi::F16>(Bt[n][k], At[m][k], acc[ai][bj][m][n]); __builtin_amdgcn_s_setprio(0); } while (0)
; #define PG8_WAIT_V(n) asm volatile("s_waitcnt vmcnt(" #n ")" ::: "memory")
; #define PG8_WAIT_L(n) asm volatile("s_waitcnt lgkmcnt(" #n ")" ::: "memory")
; template <class Epi, class Sched, bool ALIGN_EPI = false, bool SP2 = false>
; __device__ __forceinline__ void gemm_phase(PG8_LAS unsigned char* lds, const Gemm g, const Sched& S, const Epi& E, const int wave_in) {
;     ...
;         for (int t = 0; t < nt; t += 2) {
;             const bool last = (t == nt - 2);
;             const char* a1 = cA + (size_t)(t + 1) * kstep;
;             const char* a2 = last ? nA : cA + (size_t)(t + 2) * kstep; const char* b2 = last ? nB : cB + (size_t)(t + 2) * kstep;
;             const char* a3 = a2 + kstep; const char* b3 = b2 + kstep;
;             if (last && has_next) S.a_ready(nxt);
;             if constexpr (SP2) {
;             PG8_LDB(B0, 0, 0); PG8_LDB(B1, 0, 1); PG8_SCHED; PG8_LDA(At, 0, 0); PG8_STAGE(PG8_SA(1, 1), a1 + hstep, voffA);
;             PG8_WAIT_V(8); PG8_WAIT_L(0); PG8_BAR; PG8_MMA(0, 0, At, B0); PG8_MMA(0, 1, At, B1); PG8_BAR; PG8_SCHED;
;             PG8_LDA(At, 0, 1); PG8_STAGE(PG8_SB(0, 0), b2, voffB); PG8_STAGE(PG8_SB(0, 1), b2 + hstep, voffB); PG8_STAGE(PG8_SA(0, 0), a2, voffA);
;             PG8_WAIT_V(8); PG8_WAIT_L(0); PG8_BAR; PG8_MMA(1, 0, At, B0); PG8_MMA(1, 1, At, B1); PG8_BAR; PG8_SCHED;
.LBB0_859:
	v_add_u32_e32 v62, s28, v211
	v_add_u32_e32 v78, s72, v211
	ds_read_b128 v[42:45], v62
	ds_read_b128 v[46:49], v62 offset:1024
	ds_read_b128 v[54:57], v62 offset:2048
	ds_read_b128 v[62:65], v62 offset:3072
	ds_read_b128 v[66:69], v78
	ds_read_b128 v[70:73], v78 offset:1024
	ds_read_b128 v[74:77], v78 offset:2048
	ds_read_b128 v[78:81], v78 offset:3072
	s_add_u32 s14, s90, 0xfffc0080
	s_addc_u32 s15, s91, -1
	s_cmp_eq_u32 s13, 12
	s_cselect_b32 vcc_hi, s10, s15
	s_cselect_b32 vcc_lo, s11, s14
	s_cselect_b32 s37, s57, s12
	s_cselect_b32 s36, s59, s83
	v_lshl_add_u64 v[178:179], s[90:91], 0, v[220:221]
	s_add_i32 m0, s5, 0xc000
	ds_read_b128 v[98:101], v213
	ds_read_b128 v[102:105], v213 offset:1024
	ds_read_b128 v[106:109], v213 offset:2048
	ds_read_b128 v[118:121], v213 offset:3072
	ds_read_b128 v[130:133], v213 offset:4096
	ds_read_b128 v[138:141], v213 offset:5120
	ds_read_b128 v[146:149], v213 offset:6144
	ds_read_b128 v[158:161], v213 offset:7168
	global_load_lds_dwordx4 v[178:179], off
	v_lshl_add_u64 v[178:179], s[90:91], 0, v[222:223]
	s_add_i32 m0, s5, 0xe000
	s_nop 0
	global_load_lds_dwordx4 v[178:179], off
	s_waitcnt vmcnt(8)
	s_waitcnt lgkmcnt(0)
	s_barrier
	s_setprio 1
	v_mfma_f32_16x16x32_bf16 v[190:193], v[54:57], v[98:101], v[190:193]
	v_mfma_f32_16x16x32_bf16 v[174:177], v[42:45], v[106:109], v[174:177]
	v_mfma_f32_16x16x32_bf16 v[170:173], v[54:57], v[106:109], v[170:173]
	v_mfma_f32_16x16x32_bf16 v[154:157], v[42:45], v[130:133], v[154:157]
	v_mfma_f32_16x16x32_bf16 v[150:153], v[54:57], v[130:133], v[150:153]
	v_mfma_f32_16x16x32_bf16 v[126:129], v[42:45], v[146:149], v[126:129]
	v_mfma_f32_16x16x32_bf16 v[122:125], v[54:57], v[146:149], v[122:125]
	v_mfma_f32_16x16x32_bf16 v[178:181], v[42:45], v[98:101], v[194:197]
	v_mfma_f32_16x16x32_bf16 v[190:193], v[62:65], v[102:105], v[190:193]
	v_mfma_f32_16x16x32_bf16 v[174:177], v[46:49], v[118:121], v[174:177]
	v_mfma_f32_16x16x32_bf16 v[170:173], v[62:65], v[118:121], v[170:173]
	v_mfma_f32_16x16x32_bf16 v[154:157], v[46:49], v[138:141], v[154:157]
	v_mfma_f32_16x16x32_bf16 v[150:153], v[62:65], v[138:141], v[150:153]
	v_mfma_f32_16x16x32_bf16 v[126:129], v[46:49], v[158:161], v[126:129]
	v_mfma_f32_16x16x32_bf16 v[122:125], v[62:65], v[158:161], v[122:125]
	v_mfma_f32_16x16x32_bf16 v[178:181], v[46:49], v[102:105], v[178:181]
	v_mfma_f32_16x16x32_bf16 v[186:189], v[66:69], v[98:101], v[186:189]
	v_mfma_f32_16x16x32_bf16 v[98:101], v[74:77], v[98:101], v[182:185]
	v_mfma_f32_16x16x32_bf16 v[186:189], v[70:73], v[102:105], v[186:189]
	v_mfma_f32_16x16x32_bf16 v[98:101], v[78:81], v[102:105], v[98:101]
	v_mfma_f32_16x16x32_bf16 v[102:105], v[66:69], v[106:109], v[166:169]
	v_mfma_f32_16x16x32_bf16 v[106:109], v[74:77], v[106:109], v[162:165]
	v_mfma_f32_16x16x32_bf16 v[114:117], v[66:69], v[146:149], v[114:117]
	v_mfma_f32_16x16x32_bf16 v[110:113], v[74:77], v[146:149], v[110:113]
	v_mfma_f32_16x16x32_bf16 v[102:105], v[70:73], v[118:121], v[102:105]
	v_mfma_f32_16x16x32_bf16 v[106:109], v[78:81], v[118:121], v[106:109]
	v_mfma_f32_16x16x32_bf16 v[118:121], v[66:69], v[130:133], v[142:145]
	v_mfma_f32_16x16x32_bf16 v[130:133], v[74:77], v[130:133], v[134:137]
	v_mfma_f32_16x16x32_bf16 v[114:117], v[70:73], v[158:161], v[114:117]
	v_mfma_f32_16x16x32_bf16 v[110:113], v[78:81], v[158:161], v[110:113]
	v_mfma_f32_16x16x32_bf16 v[118:121], v[70:73], v[138:141], v[118:121]
	v_mfma_f32_16x16x32_bf16 v[130:133], v[78:81], v[138:141], v[130:133]
	s_setprio 0
	s_barrier
	s_add_i32 s14, s28, s4
	v_lshl_add_u64 v[228:229], s[36:37], 0, v[0:1]
	s_mov_b32 m0, s14
	ds_read_b128 v[134:137], v213 offset:16384
	ds_read_b128 v[138:141], v213 offset:17408
	ds_read_b128 v[142:145], v213 offset:18432
	ds_read_b128 v[146:149], v213 offset:19456
	ds_read_b128 v[158:161], v213 offset:20480
	ds_read_b128 v[162:165], v213 offset:21504
	ds_read_b128 v[166:169], v213 offset:22528
	ds_read_b128 v[182:185], v213 offset:23552
	global_load_lds_dwordx4 v[228:229], off
	s_add_i32 m0, s14, 0x2000
	s_add_u32 s14, s36, 0x40000
	v_lshl_add_u64 v[230:231], s[36:37], 0, v[218:219]
	s_addc_u32 s15, s37, 0
	s_add_i32 s16, s72, s4
	global_load_lds_dwordx4 v[230:231], off
	v_lshl_add_u64 v[194:195], s[14:15], 0, v[0:1]
	s_mov_b32 m0, s16
	v_lshl_add_u64 v[232:233], vcc, 0, v[214:215]
	global_load_lds_dwordx4 v[194:195], off
	v_lshl_add_u64 v[194:195], s[14:15], 0, v[218:219]
	s_add_i32 m0, s16, 0x2000
	v_lshl_add_u64 v[234:235], vcc, 0, v[216:217]
	global_load_lds_dwordx4 v[194:195], off
	s_mov_b32 m0, s5
	s_nop 0
	global_load_lds_dwordx4 v[232:233], off
	s_mov_b32 m0, s49
	s_nop 0
	global_load_lds_dwordx4 v[234:235], off
	s_waitcnt vmcnt(8)
	s_waitcnt lgkmcnt(0)
	s_barrier
; #define PG8_STAGE(bufoff, gbase, voff) do { _Pragma("unroll") for (int _i = 0; _i < 2; ++_i) \
;         __builtin_amdgcn_global_load_lds((const unsigned*)((const char*)(gbase) + (voff)[_i]), (PG8_LAS unsigned*)(lds + (bufoff) + ldsw + _i * 8192), 16, 0, 0); } while (0)
; #define PG8_LDA(dst, b, h) do { _Pragma("unroll") for (int m = 0; m < 4; ++m) _Pragma("unroll") for (int k = 0; k < 2; ++k) dst[m][k] = *(const PG8_LAS bf16x8*)(lds + PG8_SA(b, h) + aoff + m * 2048 + k * 1024); } while (0)
; #define PG8_LDB(dst, b, h) do { _Pragma("unroll") for (int n = 0; n < 2; ++n) _Pragma("unroll") for (int k = 0; k < 2; ++k) dst[n][k] = *(const PG8_LAS bf16x8*)(lds + PG8_SB(b, h) + boff + n * 2048 + k * 1024); } while (0)
; #define PG8_MMA(ai, bj, At, Bt) do { __builtin_amdgcn_s_setprio(1); _Pragma("unroll") for (int m = 0; m < 4; ++m) _Pragma("unroll") for (int n = 0; n < 2; ++n) _Pragma("unroll") for (int k = 0; k < 2; ++k) \
;         acc[ai][bj][m][n] = mma16<Epi::F16>(Bt[n][k], At[m][k], acc[ai][bj][m][n]); __builtin_amdgcn_s_setprio(0); } while (0)
; #define PG8_WAIT_V(n) asm volatile("s_waitcnt vmcnt(" #n ")" ::: "memory")
; #define PG8_WAIT_L(n) asm volatile("s_waitcnt lgkmcnt(" #n ")" ::: "memory")
; #define PG8_BAR __builtin_amdgcn_s_barrier()
; #define PG8_SCHED __builtin_amdgcn_sched_barrier(0)
; template <class Epi, class Sched, bool ALIGN_EPI = false, bool SP2 = false>
; __device__ __forceinline__ void gemm_phase(PG8_LAS unsigned char* lds, const Gemm g, const Sched& S, const Epi& E, const int wave_in) {
;     ...
;             PG8_WAIT_V(8); PG8_WAIT_L(0); PG8_BAR; PG8_MMA(1, 0, At, B0); PG8_MMA(1, 1, At, B1); PG8_BAR; PG8_SCHED;
;             PG8_LDB(B0, 1, 0); PG8_LDB(B1, 1, 1); PG8_SCHED; PG8_LDA(At, 1, 0); PG8_STAGE(PG8_SA(0, 1), a2 + hstep, voffA);
;             PG8_WAIT_V(8); PG8_WAIT_L(0); PG8_BAR; PG8_MMA(0, 0, At, B0); PG8_MMA(0, 1, At, B1); PG8_BAR; PG8_SCHED;
	s_setprio 1
	v_mfma_f32_16x16x32_bf16 v[94:97], v[42:45], v[134:137], v[94:97]
	v_mfma_f32_16x16x32_bf16 v[90:93], v[54:57], v[134:137], v[90:93]
	v_mfma_f32_16x16x32_bf16 v[58:61], v[42:45], v[142:145], v[58:61]
	v_mfma_f32_16x16x32_bf16 v[50:53], v[54:57], v[142:145], v[50:53]
	v_mfma_f32_16x16x32_bf16 v[30:33], v[42:45], v[158:161], v[30:33]
	v_mfma_f32_16x16x32_bf16 v[26:29], v[54:57], v[158:161], v[26:29]
	v_mfma_f32_16x16x32_bf16 v[14:17], v[42:45], v[166:169], v[14:17]
	v_mfma_f32_16x16x32_bf16 v[10:13], v[54:57], v[166:169], v[10:13]
	v_mfma_f32_16x16x32_bf16 v[94:97], v[46:49], v[138:141], v[94:97]
	v_mfma_f32_16x16x32_bf16 v[90:93], v[62:65], v[138:141], v[90:93]
	v_mfma_f32_16x16x32_bf16 v[58:61], v[46:49], v[146:149], v[58:61]
	v_mfma_f32_16x16x32_bf16 v[50:53], v[62:65], v[146:149], v[50:53]
	v_mfma_f32_16x16x32_bf16 v[30:33], v[46:49], v[162:165], v[30:33]
	v_mfma_f32_16x16x32_bf16 v[26:29], v[62:65], v[162:165], v[26:29]
	v_mfma_f32_16x16x32_bf16 v[14:17], v[46:49], v[182:185], v[14:17]
	v_mfma_f32_16x16x32_bf16 v[10:13], v[62:65], v[182:185], v[10:13]
	v_mfma_f32_16x16x32_bf16 v[38:41], v[66:69], v[142:145], v[38:41]
	v_mfma_f32_16x16x32_bf16 v[34:37], v[74:77], v[142:145], v[34:37]
	v_mfma_f32_16x16x32_bf16 v[22:25], v[66:69], v[158:161], v[22:25]
	v_mfma_f32_16x16x32_bf16 v[18:21], v[74:77], v[158:161], v[18:21]
	v_mfma_f32_16x16x32_bf16 v[6:9], v[66:69], v[166:169], v[6:9]
	v_mfma_f32_16x16x32_bf16 v[2:5], v[74:77], v[166:169], v[2:5]
	v_mfma_f32_16x16x32_bf16 v[42:45], v[66:69], v[134:137], v[86:89]
	v_mfma_f32_16x16x32_bf16 v[46:49], v[74:77], v[134:137], v[82:85]
	v_mfma_f32_16x16x32_bf16 v[38:41], v[70:73], v[146:149], v[38:41]
	v_mfma_f32_16x16x32_bf16 v[34:37], v[78:81], v[146:149], v[34:37]
	v_mfma_f32_16x16x32_bf16 v[22:25], v[70:73], v[162:165], v[22:25]
	v_mfma_f32_16x16x32_bf16 v[18:21], v[78:81], v[162:165], v[18:21]
	v_mfma_f32_16x16x32_bf16 v[6:9], v[70:73], v[182:185], v[6:9]
	v_mfma_f32_16x16x32_bf16 v[2:5], v[78:81], v[182:185], v[2:5]
	v_mfma_f32_16x16x32_bf16 v[42:45], v[70:73], v[138:141], v[42:45]
	v_mfma_f32_16x16x32_bf16 v[46:49], v[78:81], v[138:141], v[46:49]
	s_setprio 0
	s_barrier
	v_add_u32_e32 v70, s73, v211
	v_add_u32_e32 v82, s74, v211
	ds_read_b128 v[54:57], v70
	ds_read_b128 v[62:65], v70 offset:1024
	ds_read_b128 v[66:69], v70 offset:2048
	ds_read_b128 v[70:73], v70 offset:3072
	ds_read_b128 v[74:77], v82
	ds_read_b128 v[78:81], v82 offset:1024
	ds_read_b128 v[138:141], v82 offset:2048
	ds_read_b128 v[146:149], v82 offset:3072
	s_add_u32 s14, vcc_lo, 0x40000
	s_addc_u32 s15, vcc_hi, 0
	s_mov_b32 m0, s71
	v_lshl_add_u64 v[162:163], s[14:15], 0, v[214:215]
	ds_read_b128 v[82:85], v213 offset:32768
	ds_read_b128 v[86:89], v213 offset:33792
	ds_read_b128 v[134:137], v213 offset:34816
	ds_read_b128 v[142:145], v213 offset:35840
	ds_read_b128 v[158:161], v213 offset:36864
	ds_read_b128 v[198:201], v213 offset:37888
	ds_read_b128 v[202:205], v213 offset:38912
	ds_read_b128 v[224:227], v213 offset:39936
	global_load_lds_dwordx4 v[162:163], off
	v_lshl_add_u64 v[162:163], s[14:15], 0, v[216:217]
	s_mov_b32 m0, s82
	s_nop 0
	global_load_lds_dwordx4 v[162:163], off
	s_waitcnt vmcnt(8)
	s_waitcnt lgkmcnt(0)
	s_barrier
	s_setprio 1
	v_mfma_f32_16x16x32_bf16 v[162:165], v[54:57], v[82:85], v[178:181]
	v_mfma_f32_16x16x32_bf16 v[194:197], v[62:65], v[86:89], v[162:165]
	v_mfma_f32_16x16x32_bf16 v[162:165], v[66:69], v[82:85], v[190:193]
	v_mfma_f32_16x16x32_bf16 v[190:193], v[70:73], v[86:89], v[162:165]
	v_mfma_f32_16x16x32_bf16 v[162:165], v[54:57], v[134:137], v[174:177]
	v_mfma_f32_16x16x32_bf16 v[174:177], v[62:65], v[142:145], v[162:165]
	v_mfma_f32_16x16x32_bf16 v[162:165], v[66:69], v[134:137], v[170:173]
	v_mfma_f32_16x16x32_bf16 v[154:157], v[54:57], v[158:161], v[154:157]
	v_mfma_f32_16x16x32_bf16 v[150:153], v[66:69], v[158:161], v[150:153]
	v_mfma_f32_16x16x32_bf16 v[126:129], v[54:57], v[202:205], v[126:129]
	v_mfma_f32_16x16x32_bf16 v[122:125], v[66:69], v[202:205], v[122:125]
	v_mfma_f32_16x16x32_bf16 v[170:173], v[70:73], v[142:145], v[162:165]
	v_mfma_f32_16x16x32_bf16 v[154:157], v[62:65], v[198:201], v[154:157]
	v_mfma_f32_16x16x32_bf16 v[150:153], v[70:73], v[198:201], v[150:153]
	v_mfma_f32_16x16x32_bf16 v[126:129], v[62:65], v[224:227], v[126:129]
	v_mfma_f32_16x16x32_bf16 v[122:125], v[70:73], v[224:227], v[122:125]
	v_mfma_f32_16x16x32_bf16 v[162:165], v[74:77], v[82:85], v[186:189]
	v_mfma_f32_16x16x32_bf16 v[82:85], v[138:141], v[82:85], v[98:101]
	v_mfma_f32_16x16x32_bf16 v[182:185], v[146:149], v[86:89], v[82:85]
	v_mfma_f32_16x16x32_bf16 v[82:85], v[74:77], v[134:137], v[102:105]
	v_mfma_f32_16x16x32_bf16 v[166:169], v[78:81], v[142:145], v[82:85]
	v_mfma_f32_16x16x32_bf16 v[82:85], v[138:141], v[134:137], v[106:109]
	v_mfma_f32_16x16x32_bf16 v[186:189], v[78:81], v[86:89], v[162:165]
	v_mfma_f32_16x16x32_bf16 v[162:165], v[146:149], v[142:145], v[82:85]
	v_mfma_f32_16x16x32_bf16 v[82:85], v[74:77], v[158:161], v[118:121]
	v_mfma_f32_16x16x32_bf16 v[142:145], v[78:81], v[198:201], v[82:85]
	v_mfma_f32_16x16x32_bf16 v[82:85], v[138:141], v[158:161], v[130:133]
	v_mfma_f32_16x16x32_bf16 v[134:137], v[146:149], v[198:201], v[82:85]
	v_mfma_f32_16x16x32_bf16 v[82:85], v[74:77], v[202:205], v[114:117]
	v_mfma_f32_16x16x32_bf16 v[114:117], v[78:81], v[224:227], v[82:85]
	v_mfma_f32_16x16x32_bf16 v[82:85], v[138:141], v[202:205], v[110:113]
	v_mfma_f32_16x16x32_bf16 v[110:113], v[146:149], v[224:227], v[82:85]
	s_setprio 0
	s_barrier
; #define PG8_STAGE(bufoff, gbase, voff) do { _Pragma("unroll") for (int _i = 0; _i < 2; ++_i) \
;         __builtin_amdgcn_global_load_lds((const unsigned*)((const char*)(gbase) + (voff)[_i]), (PG8_LAS unsigned*)(lds + (bufoff) + ldsw + _i * 8192), 16, 0, 0); } while (0)
; #define PG8_LDA(dst, b, h) do { _Pragma("unroll") for (int m = 0; m < 4; ++m) _Pragma("unroll") for (int k = 0; k < 2; ++k) dst[m][k] = *(const PG8_LAS bf16x8*)(lds + PG8_SA(b, h) + aoff + m * 2048 + k * 1024); } while (0)
; #define PG8_MMA(ai, bj, At, Bt) do { __builtin_amdgcn_s_setprio(1); _Pragma("unroll") for (int m = 0; m < 4; ++m) _Pragma("unroll") for (int n = 0; n < 2; ++n) _Pragma("unroll") for (int k = 0; k < 2; ++k) \
;         acc[ai][bj][m][n] = mma16<Epi::F16>(Bt[n][k], At[m][k], acc[ai][bj][m][n]); __builtin_amdgcn_s_setprio(0); } while (0)
; #define PG8_WAIT_V(n) asm volatile("s_waitcnt vmcnt(" #n ")" ::: "memory")
; #define PG8_WAIT_L(n) asm volatile("s_waitcnt lgkmcnt(" #n ")" ::: "memory")
; #define PG8_BAR __builtin_amdgcn_s_barrier()
; #define PG8_SCHED __builtin_amdgcn_sched_barrier(0)
; template <class Epi, class Sched, bool ALIGN_EPI = false, bool SP2 = false>
; __device__ __forceinline__ void gemm_phase(PG8_LAS unsigned char* lds, const Gemm g, const Sched& S, const Epi& E, const int wave_in) {
;     ...
;         for (int t = 0; t < nt; t += 2) {
;             const bool last = (t == nt - 2);
;             const char* a1 = cA + (size_t)(t + 1) * kstep;
;             const char* a2 = last ? nA : cA + (size_t)(t + 2) * kstep; const char* b2 = last ? nB : cB + (size_t)(t + 2) * kstep;
;             const char* a3 = a2 + kstep; const char* b3 = b2 + kstep;
;             if (last && has_next) S.a_ready(nxt);
;     ...
;             PG8_LDA(At, 1, 1); PG8_STAGE(PG8_SB(1, 0), b3, voffB); PG8_STAGE(PG8_SB(1, 1), b3 + hstep, voffB); PG8_STAGE(PG8_SA(1, 0), a3, voffA);
;             PG8_WAIT_V(8); PG8_WAIT_L(0); PG8_BAR; PG8_MMA(1, 0, At, B0); PG8_MMA(1, 1, At, B1); PG8_BAR; PG8_SCHED;
	s_add_i32 s14, s73, s4
	v_lshl_add_u64 v[86:87], v[228:229], 0, s[78:79]
	s_mov_b32 m0, s14
	s_nop 1
	ds_read_b128 v[82:85], v213 offset:49152
	ds_read_b128 v[98:101], v213 offset:50176
	ds_read_b128 v[102:105], v213 offset:51200
	ds_read_b128 v[106:109], v213 offset:52224
	ds_read_b128 v[118:121], v213 offset:53248
	ds_read_b128 v[130:133], v213 offset:54272
	ds_read_b128 v[158:161], v213 offset:55296
	ds_read_b128 v[178:181], v213 offset:56320
	global_load_lds_dwordx4 v[86:87], off
	s_add_i32 m0, s14, 0x2000
	s_add_u32 s14, s36, 0x40080
	v_lshl_add_u64 v[86:87], v[230:231], 0, s[78:79]
	s_addc_u32 s15, s37, 0
	s_add_i32 s16, s74, s4
	global_load_lds_dwordx4 v[86:87], off
	v_lshl_add_u64 v[86:87], s[14:15], 0, v[0:1]
	s_mov_b32 m0, s16
	s_nop 0
	global_load_lds_dwordx4 v[86:87], off
	v_lshl_add_u64 v[86:87], s[14:15], 0, v[218:219]
	s_add_i32 m0, s16, 0x2000
	s_nop 0
	global_load_lds_dwordx4 v[86:87], off
	v_lshl_add_u64 v[86:87], v[232:233], 0, s[78:79]
	s_mov_b32 m0, s6
	s_nop 0
	global_load_lds_dwordx4 v[86:87], off
	v_lshl_add_u64 v[86:87], v[234:235], 0, s[78:79]
	s_mov_b32 m0, s7
	s_nop 0
	global_load_lds_dwordx4 v[86:87], off
	s_waitcnt vmcnt(8)
	s_waitcnt lgkmcnt(0)
	s_barrier
	s_setprio 1
	v_mfma_f32_16x16x32_bf16 v[86:89], v[54:57], v[82:85], v[94:97]
	v_mfma_f32_16x16x32_bf16 v[94:97], v[62:65], v[98:101], v[86:89]
	v_mfma_f32_16x16x32_bf16 v[86:89], v[66:69], v[82:85], v[90:93]
	v_mfma_f32_16x16x32_bf16 v[58:61], v[54:57], v[102:105], v[58:61]
	v_mfma_f32_16x16x32_bf16 v[50:53], v[66:69], v[102:105], v[50:53]
	v_mfma_f32_16x16x32_bf16 v[30:33], v[54:57], v[118:121], v[30:33]
	v_mfma_f32_16x16x32_bf16 v[26:29], v[66:69], v[118:121], v[26:29]
	v_mfma_f32_16x16x32_bf16 v[14:17], v[54:57], v[158:161], v[14:17]
	v_mfma_f32_16x16x32_bf16 v[10:13], v[66:69], v[158:161], v[10:13]
	v_mfma_f32_16x16x32_bf16 v[90:93], v[70:73], v[98:101], v[86:89]
	v_mfma_f32_16x16x32_bf16 v[58:61], v[62:65], v[106:109], v[58:61]
	v_mfma_f32_16x16x32_bf16 v[50:53], v[70:73], v[106:109], v[50:53]
	v_mfma_f32_16x16x32_bf16 v[30:33], v[62:65], v[130:133], v[30:33]
	v_mfma_f32_16x16x32_bf16 v[26:29], v[70:73], v[130:133], v[26:29]
	v_mfma_f32_16x16x32_bf16 v[14:17], v[62:65], v[178:181], v[14:17]
	v_mfma_f32_16x16x32_bf16 v[10:13], v[70:73], v[178:181], v[10:13]
	v_mfma_f32_16x16x32_bf16 v[42:45], v[74:77], v[82:85], v[42:45]
	v_mfma_f32_16x16x32_bf16 v[86:89], v[78:81], v[98:101], v[42:45]
	v_mfma_f32_16x16x32_bf16 v[42:45], v[138:141], v[82:85], v[46:49]
	v_mfma_f32_16x16x32_bf16 v[38:41], v[74:77], v[102:105], v[38:41]
	v_mfma_f32_16x16x32_bf16 v[34:37], v[138:141], v[102:105], v[34:37]
	v_mfma_f32_16x16x32_bf16 v[22:25], v[74:77], v[118:121], v[22:25]
	v_mfma_f32_16x16x32_bf16 v[18:21], v[138:141], v[118:121], v[18:21]
	v_mfma_f32_16x16x32_bf16 v[6:9], v[74:77], v[158:161], v[6:9]
	v_mfma_f32_16x16x32_bf16 v[2:5], v[138:141], v[158:161], v[2:5]
	v_mfma_f32_16x16x32_bf16 v[82:85], v[146:149], v[98:101], v[42:45]
	v_mfma_f32_16x16x32_bf16 v[38:41], v[78:81], v[106:109], v[38:41]
	v_mfma_f32_16x16x32_bf16 v[34:37], v[146:149], v[106:109], v[34:37]
	v_mfma_f32_16x16x32_bf16 v[22:25], v[78:81], v[130:133], v[22:25]
	v_mfma_f32_16x16x32_bf16 v[18:21], v[146:149], v[130:133], v[18:21]
	v_mfma_f32_16x16x32_bf16 v[6:9], v[78:81], v[178:181], v[6:9]
	v_mfma_f32_16x16x32_bf16 v[2:5], v[146:149], v[178:181], v[2:5]
	s_setprio 0
	s_barrier
	s_add_i32 s13, s13, 2
	s_add_u32 s90, s90, 0x100
	s_addc_u32 s91, s91, 0
	s_add_u32 s83, s83, 0x100
	s_addc_u32 s12, s12, 0
	s_cmp_gt_u32 s13, 13
	s_cbranch_scc0 .LBB0_859
	s_and_b64 vcc, exec, s[54:55]
	s_cbranch_vccz .LBB0_862
	s_barrier

; #define PG8_STAGE(bufoff, gbase, voff) do { _Pragma("unroll") for (int _i = 0; _i < 2; ++_i) \
;         __builtin_amdgcn_global_load_lds((const unsigned*)((const char*)(gbase) + (voff)[_i]), (PG8_LAS unsigned*)(lds + (bufoff) + ldsw + _i * 8192), 16, 0, 0); } while (0)
; #define PG8_LDA(dst, b, h) do { _Pragma("unroll") for (int m = 0; m < 4; ++m) _Pragma("unroll") for (int k = 0; k < 2; ++k) dst[m][k] = *(const PG8_LAS bf16x8*)(lds + PG8_SA(b, h) + aoff + m * 2048 + k * 1024); } while (0)
; #define PG8_LDB(dst, b, h) do { _Pragma("unroll") for (int n = 0; n < 2; ++n) _Pragma("unroll") for (int k = 0; k < 2; ++k) dst[n][k] = *(const PG8_LAS bf16x8*)(lds + PG8_SB(b, h) + boff + n * 2048 + k * 1024); } while (0)
; #define PG8_MMA(ai, bj, At, Bt) do { __builtin_amdgcn_s_setprio(1); _Pragma("unroll") for (int m = 0; m < 4; ++m) _Pragma("unroll") for (int n = 0; n < 2; ++n) _Pragma("unroll") for (int k = 0; k < 2; ++k) \
;         acc[ai][bj][m][n] = mma16<Epi::F16>(Bt[n][k], At[m][k], acc[ai][bj][m][n]); __builtin_amdgcn_s_setprio(0); } while (0)
; #define PG8_WAIT_V(n) asm volatile("s_waitcnt vmcnt(" #n ")" ::: "memory")
; #define PG8_WAIT_L(n) asm volatile("s_waitcnt lgkmcnt(" #n ")" ::: "memory")
; template <class Epi, class Sched, bool ALIGN_EPI = false, bool SP2 = false>
; __device__ __forceinline__ void gemm_phase(PG8_LAS unsigned char* lds, const Gemm g, const Sched& S, const Epi& E, const int wave_in) {
;     ...
;         for (int t = 0; t < nt; t += 2) {
;             const bool last = (t == nt - 2);
;             const char* a1 = cA + (size_t)(t + 1) * kstep;
;             const char* a2 = last ? nA : cA + (size_t)(t + 2) * kstep; const char* b2 = last ? nB : cB + (size_t)(t + 2) * kstep;
;             const char* a3 = a2 + kstep; const char* b3 = b2 + kstep;
;             if (last && has_next) S.a_ready(nxt);
;             if constexpr (SP2) {
;             PG8_LDB(B0, 0, 0); PG8_LDB(B1, 0, 1); PG8_SCHED; PG8_LDA(At, 0, 0); PG8_STAGE(PG8_SA(1, 1), a1 + hstep, voffA);
;             PG8_WAIT_V(8); PG8_WAIT_L(0); PG8_BAR; PG8_MMA(0, 0, At, B0); PG8_MMA(0, 1, At, B1); PG8_BAR; PG8_SCHED;
;             PG8_LDA(At, 0, 1); PG8_STAGE(PG8_SB(0, 0), b2, voffB); PG8_STAGE(PG8_SB(0, 1), b2 + hstep, voffB); PG8_STAGE(PG8_SA(0, 0), a2, voffA);
;             PG8_WAIT_V(8); PG8_WAIT_L(0); PG8_BAR; PG8_MMA(1, 0, At, B0); PG8_MMA(1, 1, At, B1); PG8_BAR; PG8_SCHED;
.LBB0_1035:
	v_add_u32_e32 v130, s28, v179
	v_add_u32_e32 v154, s72, v179
	ds_read_b128 v[114:117], v130
	ds_read_b128 v[118:121], v130 offset:1024
	ds_read_b128 v[122:125], v130 offset:2048
	ds_read_b128 v[130:133], v130 offset:3072
	ds_read_b128 v[138:141], v154
	ds_read_b128 v[142:145], v154 offset:1024
	ds_read_b128 v[146:149], v154 offset:2048
	ds_read_b128 v[154:157], v154 offset:3072
	s_add_u32 s14, s60, 0xfffc0080
	s_addc_u32 s15, s61, -1
	s_cmp_eq_u32 s13, 12
	s_cselect_b32 s63, s10, s15
	s_cselect_b32 s62, s11, s14
	s_cselect_b32 s37, s53, s12
	s_cselect_b32 s36, s55, s83
	v_lshl_add_u64 v[204:205], s[60:61], 0, v[168:169]
	s_add_i32 m0, s5, 0xc000
	ds_read_b128 v[172:175], v183
	ds_read_b128 v[184:187], v183 offset:1024
	ds_read_b128 v[188:191], v183 offset:2048
	ds_read_b128 v[192:195], v183 offset:3072
	ds_read_b128 v[196:199], v183 offset:4096
	ds_read_b128 v[200:203], v183 offset:5120
	ds_read_b128 v[210:213], v183 offset:6144
	ds_read_b128 v[214:217], v183 offset:7168
	global_load_lds_dwordx4 v[204:205], off
	v_lshl_add_u64 v[204:205], s[60:61], 0, v[170:171]
	s_add_i32 m0, s5, 0xe000
	s_nop 0
	global_load_lds_dwordx4 v[204:205], off
	s_waitcnt vmcnt(8)
	s_waitcnt lgkmcnt(0)
	s_barrier
	s_setprio 1
	v_mfma_f32_16x16x32_f16 v[158:161], v[114:117], v[172:175], v[158:161]
	v_mfma_f32_16x16x32_f16 v[150:153], v[122:125], v[172:175], v[150:153]
	v_mfma_f32_16x16x32_f16 v[110:113], v[114:117], v[188:191], v[110:113]
	v_mfma_f32_16x16x32_f16 v[106:109], v[122:125], v[188:191], v[106:109]
	v_mfma_f32_16x16x32_f16 v[94:97], v[114:117], v[196:199], v[94:97]
	v_mfma_f32_16x16x32_f16 v[90:93], v[122:125], v[196:199], v[90:93]
	v_mfma_f32_16x16x32_f16 v[78:81], v[114:117], v[210:213], v[78:81]
	v_mfma_f32_16x16x32_f16 v[74:77], v[122:125], v[210:213], v[74:77]
	v_mfma_f32_16x16x32_f16 v[158:161], v[118:121], v[184:187], v[158:161]
	v_mfma_f32_16x16x32_f16 v[150:153], v[130:133], v[184:187], v[150:153]
	v_mfma_f32_16x16x32_f16 v[110:113], v[118:121], v[192:195], v[110:113]
	v_mfma_f32_16x16x32_f16 v[106:109], v[130:133], v[192:195], v[106:109]
	v_mfma_f32_16x16x32_f16 v[94:97], v[118:121], v[200:203], v[94:97]
	v_mfma_f32_16x16x32_f16 v[90:93], v[130:133], v[200:203], v[90:93]
	v_mfma_f32_16x16x32_f16 v[78:81], v[118:121], v[214:217], v[78:81]
	v_mfma_f32_16x16x32_f16 v[74:77], v[130:133], v[214:217], v[74:77]
	v_mfma_f32_16x16x32_f16 v[134:137], v[138:141], v[172:175], v[134:137]
	v_mfma_f32_16x16x32_f16 v[126:129], v[146:149], v[172:175], v[126:129]
	v_mfma_f32_16x16x32_f16 v[102:105], v[138:141], v[188:191], v[102:105]
	v_mfma_f32_16x16x32_f16 v[98:101], v[146:149], v[188:191], v[98:101]
	v_mfma_f32_16x16x32_f16 v[86:89], v[138:141], v[196:199], v[86:89]
	v_mfma_f32_16x16x32_f16 v[82:85], v[146:149], v[196:199], v[82:85]
	v_mfma_f32_16x16x32_f16 v[70:73], v[138:141], v[210:213], v[70:73]
	v_mfma_f32_16x16x32_f16 v[66:69], v[146:149], v[210:213], v[66:69]
	v_mfma_f32_16x16x32_f16 v[134:137], v[142:145], v[184:187], v[134:137]
	v_mfma_f32_16x16x32_f16 v[126:129], v[154:157], v[184:187], v[126:129]
	v_mfma_f32_16x16x32_f16 v[102:105], v[142:145], v[192:195], v[102:105]
	v_mfma_f32_16x16x32_f16 v[98:101], v[154:157], v[192:195], v[98:101]
	v_mfma_f32_16x16x32_f16 v[86:89], v[142:145], v[200:203], v[86:89]
	v_mfma_f32_16x16x32_f16 v[82:85], v[154:157], v[200:203], v[82:85]
	v_mfma_f32_16x16x32_f16 v[70:73], v[142:145], v[214:217], v[70:73]
	v_mfma_f32_16x16x32_f16 v[66:69], v[154:157], v[214:217], v[66:69]
	s_setprio 0
	s_barrier
	s_add_i32 s14, s28, s4
	v_lshl_add_u64 v[204:205], s[36:37], 0, v[0:1]
	s_mov_b32 m0, s14
	ds_read_b128 v[172:175], v183 offset:16384
	ds_read_b128 v[184:187], v183 offset:17408
	ds_read_b128 v[188:191], v183 offset:18432
	ds_read_b128 v[192:195], v183 offset:19456
	ds_read_b128 v[196:199], v183 offset:20480
	ds_read_b128 v[200:203], v183 offset:21504
	ds_read_b128 v[210:213], v183 offset:22528
	ds_read_b128 v[214:217], v183 offset:23552
	global_load_lds_dwordx4 v[204:205], off
	s_add_i32 m0, s14, 0x2000
	s_add_u32 s14, s36, 0x40000
	v_lshl_add_u64 v[218:219], s[36:37], 0, v[166:167]
	s_addc_u32 s15, s37, 0
	s_add_i32 s16, s72, s4
	global_load_lds_dwordx4 v[218:219], off
	v_lshl_add_u64 v[220:221], s[14:15], 0, v[0:1]
	s_mov_b32 m0, s16
	v_lshl_add_u64 v[222:223], s[62:63], 0, v[164:165]
	global_load_lds_dwordx4 v[220:221], off
	v_lshl_add_u64 v[220:221], s[14:15], 0, v[166:167]
	s_add_i32 m0, s16, 0x2000
	s_nop 0
	global_load_lds_dwordx4 v[220:221], off
	v_lshl_add_u64 v[220:221], s[62:63], 0, v[162:163]
	s_mov_b32 m0, s5
	s_nop 0
	global_load_lds_dwordx4 v[220:221], off
	s_mov_b32 m0, s6
	s_nop 0
	global_load_lds_dwordx4 v[222:223], off
	s_waitcnt vmcnt(8)
	s_waitcnt lgkmcnt(0)
	s_barrier
; #define PG8_STAGE(bufoff, gbase, voff) do { _Pragma("unroll") for (int _i = 0; _i < 2; ++_i) \
;         __builtin_amdgcn_global_load_lds((const unsigned*)((const char*)(gbase) + (voff)[_i]), (PG8_LAS unsigned*)(lds + (bufoff) + ldsw + _i * 8192), 16, 0, 0); } while (0)
; #define PG8_LDA(dst, b, h) do { _Pragma("unroll") for (int m = 0; m < 4; ++m) _Pragma("unroll") for (int k = 0; k < 2; ++k) dst[m][k] = *(const PG8_LAS bf16x8*)(lds + PG8_SA(b, h) + aoff + m * 2048 + k * 1024); } while (0)
; #define PG8_LDB(dst, b, h) do { _Pragma("unroll") for (int n = 0; n < 2; ++n) _Pragma("unroll") for (int k = 0; k < 2; ++k) dst[n][k] = *(const PG8_LAS bf16x8*)(lds + PG8_SB(b, h) + boff + n * 2048 + k * 1024); } while (0)
; #define PG8_MMA(ai, bj, At, Bt) do { __builtin_amdgcn_s_setprio(1); _Pragma("unroll") for (int m = 0; m < 4; ++m) _Pragma("unroll") for (int n = 0; n < 2; ++n) _Pragma("unroll") for (int k = 0; k < 2; ++k) \
;         acc[ai][bj][m][n] = mma16<Epi::F16>(Bt[n][k], At[m][k], acc[ai][bj][m][n]); __builtin_amdgcn_s_setprio(0); } while (0)
; #define PG8_WAIT_V(n) asm volatile("s_waitcnt vmcnt(" #n ")" ::: "memory")
; #define PG8_WAIT_L(n) asm volatile("s_waitcnt lgkmcnt(" #n ")" ::: "memory")
; #define PG8_BAR __builtin_amdgcn_s_barrier()
; #define PG8_SCHED __builtin_amdgcn_sched_barrier(0)
; template <class Epi, class Sched, bool ALIGN_EPI = false, bool SP2 = false>
; __device__ __forceinline__ void gemm_phase(PG8_LAS unsigned char* lds, const Gemm g, const Sched& S, const Epi& E, const int wave_in) {
;     ...
;             PG8_WAIT_V(8); PG8_WAIT_L(0); PG8_BAR; PG8_MMA(1, 0, At, B0); PG8_MMA(1, 1, At, B1); PG8_BAR; PG8_SCHED;
;             PG8_LDB(B0, 1, 0); PG8_LDB(B1, 1, 1); PG8_SCHED; PG8_LDA(At, 1, 0); PG8_STAGE(PG8_SA(0, 1), a2 + hstep, voffA);
;             PG8_WAIT_V(8); PG8_WAIT_L(0); PG8_BAR; PG8_MMA(0, 0, At, B0); PG8_MMA(0, 1, At, B1); PG8_BAR; PG8_SCHED;
	s_setprio 1
	v_mfma_f32_16x16x32_f16 v[62:65], v[114:117], v[172:175], v[62:65]
	v_mfma_f32_16x16x32_f16 v[58:61], v[122:125], v[172:175], v[58:61]
	v_mfma_f32_16x16x32_f16 v[46:49], v[114:117], v[188:191], v[46:49]
	v_mfma_f32_16x16x32_f16 v[42:45], v[122:125], v[188:191], v[42:45]
	v_mfma_f32_16x16x32_f16 v[30:33], v[114:117], v[196:199], v[30:33]
	v_mfma_f32_16x16x32_f16 v[26:29], v[122:125], v[196:199], v[26:29]
	v_mfma_f32_16x16x32_f16 v[14:17], v[114:117], v[210:213], v[14:17]
	v_mfma_f32_16x16x32_f16 v[10:13], v[122:125], v[210:213], v[10:13]
	v_mfma_f32_16x16x32_f16 v[62:65], v[118:121], v[184:187], v[62:65]
	v_mfma_f32_16x16x32_f16 v[58:61], v[130:133], v[184:187], v[58:61]
	v_mfma_f32_16x16x32_f16 v[46:49], v[118:121], v[192:195], v[46:49]
	v_mfma_f32_16x16x32_f16 v[42:45], v[130:133], v[192:195], v[42:45]
	v_mfma_f32_16x16x32_f16 v[30:33], v[118:121], v[200:203], v[30:33]
	v_mfma_f32_16x16x32_f16 v[26:29], v[130:133], v[200:203], v[26:29]
	v_mfma_f32_16x16x32_f16 v[14:17], v[118:121], v[214:217], v[14:17]
	v_mfma_f32_16x16x32_f16 v[10:13], v[130:133], v[214:217], v[10:13]
	v_mfma_f32_16x16x32_f16 v[54:57], v[138:141], v[172:175], v[54:57]
	v_mfma_f32_16x16x32_f16 v[50:53], v[146:149], v[172:175], v[50:53]
	v_mfma_f32_16x16x32_f16 v[38:41], v[138:141], v[188:191], v[38:41]
	v_mfma_f32_16x16x32_f16 v[34:37], v[146:149], v[188:191], v[34:37]
	v_mfma_f32_16x16x32_f16 v[22:25], v[138:141], v[196:199], v[22:25]
	v_mfma_f32_16x16x32_f16 v[18:21], v[146:149], v[196:199], v[18:21]
	v_mfma_f32_16x16x32_f16 v[6:9], v[138:141], v[210:213], v[6:9]
	v_mfma_f32_16x16x32_f16 v[2:5], v[146:149], v[210:213], v[2:5]
	v_mfma_f32_16x16x32_f16 v[54:57], v[142:145], v[184:187], v[54:57]
	v_mfma_f32_16x16x32_f16 v[50:53], v[154:157], v[184:187], v[50:53]
	v_mfma_f32_16x16x32_f16 v[38:41], v[142:145], v[192:195], v[38:41]
	v_mfma_f32_16x16x32_f16 v[34:37], v[154:157], v[192:195], v[34:37]
	v_mfma_f32_16x16x32_f16 v[22:25], v[142:145], v[200:203], v[22:25]
	v_mfma_f32_16x16x32_f16 v[18:21], v[154:157], v[200:203], v[18:21]
	v_mfma_f32_16x16x32_f16 v[6:9], v[142:145], v[214:217], v[6:9]
	v_mfma_f32_16x16x32_f16 v[2:5], v[154:157], v[214:217], v[2:5]
	s_setprio 0
	s_barrier
	v_add_u32_e32 v130, s73, v179
	v_add_u32_e32 v154, s74, v179
	ds_read_b128 v[114:117], v130
	ds_read_b128 v[118:121], v130 offset:1024
	ds_read_b128 v[122:125], v130 offset:2048
	ds_read_b128 v[130:133], v130 offset:3072
	ds_read_b128 v[138:141], v154
	ds_read_b128 v[142:145], v154 offset:1024
	ds_read_b128 v[146:149], v154 offset:2048
	ds_read_b128 v[154:157], v154 offset:3072
	s_add_u32 s14, s62, 0x40000
	s_addc_u32 s15, s63, 0
	s_mov_b32 m0, s7
	v_lshl_add_u64 v[224:225], s[14:15], 0, v[162:163]
	ds_read_b128 v[172:175], v183 offset:32768
	ds_read_b128 v[184:187], v183 offset:33792
	ds_read_b128 v[188:191], v183 offset:34816
	ds_read_b128 v[192:195], v183 offset:35840
	ds_read_b128 v[196:199], v183 offset:36864
	ds_read_b128 v[200:203], v183 offset:37888
	ds_read_b128 v[210:213], v183 offset:38912
	ds_read_b128 v[214:217], v183 offset:39936
	global_load_lds_dwordx4 v[224:225], off
	v_lshl_add_u64 v[224:225], s[14:15], 0, v[164:165]
	s_mov_b32 m0, s8
	s_nop 0
	global_load_lds_dwordx4 v[224:225], off
	s_waitcnt vmcnt(8)
	s_waitcnt lgkmcnt(0)
	s_barrier
	s_setprio 1
	v_mfma_f32_16x16x32_f16 v[158:161], v[114:117], v[172:175], v[158:161]
	v_mfma_f32_16x16x32_f16 v[150:153], v[122:125], v[172:175], v[150:153]
	v_mfma_f32_16x16x32_f16 v[110:113], v[114:117], v[188:191], v[110:113]
	v_mfma_f32_16x16x32_f16 v[106:109], v[122:125], v[188:191], v[106:109]
	v_mfma_f32_16x16x32_f16 v[94:97], v[114:117], v[196:199], v[94:97]
	v_mfma_f32_16x16x32_f16 v[90:93], v[122:125], v[196:199], v[90:93]
	v_mfma_f32_16x16x32_f16 v[78:81], v[114:117], v[210:213], v[78:81]
	v_mfma_f32_16x16x32_f16 v[74:77], v[122:125], v[210:213], v[74:77]
	v_mfma_f32_16x16x32_f16 v[158:161], v[118:121], v[184:187], v[158:161]
	v_mfma_f32_16x16x32_f16 v[150:153], v[130:133], v[184:187], v[150:153]
	v_mfma_f32_16x16x32_f16 v[110:113], v[118:121], v[192:195], v[110:113]
	v_mfma_f32_16x16x32_f16 v[106:109], v[130:133], v[192:195], v[106:109]
	v_mfma_f32_16x16x32_f16 v[94:97], v[118:121], v[200:203], v[94:97]
	v_mfma_f32_16x16x32_f16 v[90:93], v[130:133], v[200:203], v[90:93]
	v_mfma_f32_16x16x32_f16 v[78:81], v[118:121], v[214:217], v[78:81]
	v_mfma_f32_16x16x32_f16 v[74:77], v[130:133], v[214:217], v[74:77]
	v_mfma_f32_16x16x32_f16 v[134:137], v[138:141], v[172:175], v[134:137]
	v_mfma_f32_16x16x32_f16 v[126:129], v[146:149], v[172:175], v[126:129]
	v_mfma_f32_16x16x32_f16 v[102:105], v[138:141], v[188:191], v[102:105]
	v_mfma_f32_16x16x32_f16 v[98:101], v[146:149], v[188:191], v[98:101]
	v_mfma_f32_16x16x32_f16 v[86:89], v[138:141], v[196:199], v[86:89]
	v_mfma_f32_16x16x32_f16 v[82:85], v[146:149], v[196:199], v[82:85]
	v_mfma_f32_16x16x32_f16 v[70:73], v[138:141], v[210:213], v[70:73]
	v_mfma_f32_16x16x32_f16 v[66:69], v[146:149], v[210:213], v[66:69]
	v_mfma_f32_16x16x32_f16 v[134:137], v[142:145], v[184:187], v[134:137]
	v_mfma_f32_16x16x32_f16 v[126:129], v[154:157], v[184:187], v[126:129]
	v_mfma_f32_16x16x32_f16 v[102:105], v[142:145], v[192:195], v[102:105]
	v_mfma_f32_16x16x32_f16 v[98:101], v[154:157], v[192:195], v[98:101]
	v_mfma_f32_16x16x32_f16 v[86:89], v[142:145], v[200:203], v[86:89]
	v_mfma_f32_16x16x32_f16 v[82:85], v[154:157], v[200:203], v[82:85]
	v_mfma_f32_16x16x32_f16 v[70:73], v[142:145], v[214:217], v[70:73]
	v_mfma_f32_16x16x32_f16 v[66:69], v[154:157], v[214:217], v[66:69]
	s_setprio 0
	s_barrier
; #define PG8_STAGE(bufoff, gbase, voff) do { _Pragma("unroll") for (int _i = 0; _i < 2; ++_i) \
;         __builtin_amdgcn_global_load_lds((const unsigned*)((const char*)(gbase) + (voff)[_i]), (PG8_LAS unsigned*)(lds + (bufoff) + ldsw + _i * 8192), 16, 0, 0); } while (0)
; #define PG8_LDA(dst, b, h) do { _Pragma("unroll") for (int m = 0; m < 4; ++m) _Pragma("unroll") for (int k = 0; k < 2; ++k) dst[m][k] = *(const PG8_LAS bf16x8*)(lds + PG8_SA(b, h) + aoff + m * 2048 + k * 1024); } while (0)
; #define PG8_MMA(ai, bj, At, Bt) do { __builtin_amdgcn_s_setprio(1); _Pragma("unroll") for (int m = 0; m < 4; ++m) _Pragma("unroll") for (int n = 0; n < 2; ++n) _Pragma("unroll") for (int k = 0; k < 2; ++k) \
;         acc[ai][bj][m][n] = mma16<Epi::F16>(Bt[n][k], At[m][k], acc[ai][bj][m][n]); __builtin_amdgcn_s_setprio(0); } while (0)
; #define PG8_WAIT_V(n) asm volatile("s_waitcnt vmcnt(" #n ")" ::: "memory")
; #define PG8_WAIT_L(n) asm volatile("s_waitcnt lgkmcnt(" #n ")" ::: "memory")
; #define PG8_BAR __builtin_amdgcn_s_barrier()
; #define PG8_SCHED __builtin_amdgcn_sched_barrier(0)
; template <class Epi, class Sched, bool ALIGN_EPI = false, bool SP2 = false>
; __device__ __forceinline__ void gemm_phase(PG8_LAS unsigned char* lds, const Gemm g, const Sched& S, const Epi& E, const int wave_in) {
;     ...
;         for (int t = 0; t < nt; t += 2) {
;             const bool last = (t == nt - 2);
;             const char* a1 = cA + (size_t)(t + 1) * kstep;
;             const char* a2 = last ? nA : cA + (size_t)(t + 2) * kstep; const char* b2 = last ? nB : cB + (size_t)(t + 2) * kstep;
;             const char* a3 = a2 + kstep; const char* b3 = b2 + kstep;
;     ...
;             PG8_LDA(At, 1, 1); PG8_STAGE(PG8_SB(1, 0), b3, voffB); PG8_STAGE(PG8_SB(1, 1), b3 + hstep, voffB); PG8_STAGE(PG8_SA(1, 0), a3, voffA);
;             PG8_WAIT_V(8); PG8_WAIT_L(0); PG8_BAR; PG8_MMA(1, 0, At, B0); PG8_MMA(1, 1, At, B1); PG8_BAR; PG8_SCHED;
	s_add_i32 s14, s73, s4
	v_lshl_add_u64 v[204:205], v[204:205], 0, s[78:79]
	s_mov_b32 m0, s14
	ds_read_b128 v[172:175], v183 offset:49152
	ds_read_b128 v[184:187], v183 offset:50176
	ds_read_b128 v[188:191], v183 offset:51200
	ds_read_b128 v[192:195], v183 offset:52224
	ds_read_b128 v[196:199], v183 offset:53248
	ds_read_b128 v[200:203], v183 offset:54272
	ds_read_b128 v[210:213], v183 offset:55296
	ds_read_b128 v[214:217], v183 offset:56320
	global_load_lds_dwordx4 v[204:205], off
	s_add_i32 m0, s14, 0x2000
	s_add_u32 s14, s36, 0x40080
	v_lshl_add_u64 v[204:205], v[218:219], 0, s[78:79]
	s_addc_u32 s15, s37, 0
	s_add_i32 s16, s74, s4
	global_load_lds_dwordx4 v[204:205], off
	v_lshl_add_u64 v[204:205], s[14:15], 0, v[0:1]
	s_mov_b32 m0, s16
	s_nop 0
	global_load_lds_dwordx4 v[204:205], off
	v_lshl_add_u64 v[204:205], s[14:15], 0, v[166:167]
	s_add_i32 m0, s16, 0x2000
	s_nop 0
	global_load_lds_dwordx4 v[204:205], off
	v_lshl_add_u64 v[204:205], v[220:221], 0, s[78:79]
	s_mov_b32 m0, s9
	s_nop 0
	global_load_lds_dwordx4 v[204:205], off
	v_lshl_add_u64 v[204:205], v[222:223], 0, s[78:79]
	s_mov_b32 m0, s49
	s_nop 0
	global_load_lds_dwordx4 v[204:205], off
	s_waitcnt vmcnt(8)
	s_waitcnt lgkmcnt(0)
	s_barrier
	s_setprio 1
	v_mfma_f32_16x16x32_f16 v[62:65], v[114:117], v[172:175], v[62:65]
	v_mfma_f32_16x16x32_f16 v[58:61], v[122:125], v[172:175], v[58:61]
	v_mfma_f32_16x16x32_f16 v[46:49], v[114:117], v[188:191], v[46:49]
	v_mfma_f32_16x16x32_f16 v[42:45], v[122:125], v[188:191], v[42:45]
	v_mfma_f32_16x16x32_f16 v[30:33], v[114:117], v[196:199], v[30:33]
	v_mfma_f32_16x16x32_f16 v[26:29], v[122:125], v[196:199], v[26:29]
	v_mfma_f32_16x16x32_f16 v[14:17], v[114:117], v[210:213], v[14:17]
	v_mfma_f32_16x16x32_f16 v[10:13], v[122:125], v[210:213], v[10:13]
	v_mfma_f32_16x16x32_f16 v[62:65], v[118:121], v[184:187], v[62:65]
	v_mfma_f32_16x16x32_f16 v[58:61], v[130:133], v[184:187], v[58:61]
	v_mfma_f32_16x16x32_f16 v[46:49], v[118:121], v[192:195], v[46:49]
	v_mfma_f32_16x16x32_f16 v[42:45], v[130:133], v[192:195], v[42:45]
	v_mfma_f32_16x16x32_f16 v[30:33], v[118:121], v[200:203], v[30:33]
	v_mfma_f32_16x16x32_f16 v[26:29], v[130:133], v[200:203], v[26:29]
	v_mfma_f32_16x16x32_f16 v[14:17], v[118:121], v[214:217], v[14:17]
	v_mfma_f32_16x16x32_f16 v[10:13], v[130:133], v[214:217], v[10:13]
	v_mfma_f32_16x16x32_f16 v[54:57], v[138:141], v[172:175], v[54:57]
	v_mfma_f32_16x16x32_f16 v[50:53], v[146:149], v[172:175], v[50:53]
	v_mfma_f32_16x16x32_f16 v[38:41], v[138:141], v[188:191], v[38:41]
	v_mfma_f32_16x16x32_f16 v[34:37], v[146:149], v[188:191], v[34:37]
	v_mfma_f32_16x16x32_f16 v[22:25], v[138:141], v[196:199], v[22:25]
	v_mfma_f32_16x16x32_f16 v[18:21], v[146:149], v[196:199], v[18:21]
	v_mfma_f32_16x16x32_f16 v[6:9], v[138:141], v[210:213], v[6:9]
	v_mfma_f32_16x16x32_f16 v[2:5], v[146:149], v[210:213], v[2:5]
	v_mfma_f32_16x16x32_f16 v[54:57], v[142:145], v[184:187], v[54:57]
	v_mfma_f32_16x16x32_f16 v[50:53], v[154:157], v[184:187], v[50:53]
	v_mfma_f32_16x16x32_f16 v[38:41], v[142:145], v[192:195], v[38:41]
	v_mfma_f32_16x16x32_f16 v[34:37], v[154:157], v[192:195], v[34:37]
	v_mfma_f32_16x16x32_f16 v[22:25], v[142:145], v[200:203], v[22:25]
	v_mfma_f32_16x16x32_f16 v[18:21], v[154:157], v[200:203], v[18:21]
	v_mfma_f32_16x16x32_f16 v[6:9], v[142:145], v[214:217], v[6:9]
	v_mfma_f32_16x16x32_f16 v[2:5], v[154:157], v[214:217], v[2:5]
	s_setprio 0
	s_barrier
	s_add_i32 s13, s13, 2
	s_add_u32 s60, s60, 0x100
	s_addc_u32 s61, s61, 0
	s_add_u32 s83, s83, 0x100
	s_addc_u32 s12, s12, 0
	s_cmp_gt_u32 s13, 13
	s_cbranch_scc0 .LBB0_1035
	s_and_b64 vcc, exec, s[50:51]
	s_cbranch_vccz .LBB0_1038
	s_barrier

; #define PG8_STAGE(bufoff, gbase, voff) do { _Pragma("unroll") for (int _i = 0; _i < 2; ++_i) \
;         __builtin_amdgcn_global_load_lds((const unsigned*)((const char*)(gbase) + (voff)[_i]), (PG8_LAS unsigned*)(lds + (bufoff) + ldsw + _i * 8192), 16, 0, 0); } while (0)
; #define PG8_LDA(dst, b, h) do { _Pragma("unroll") for (int m = 0; m < 4; ++m) _Pragma("unroll") for (int k = 0; k < 2; ++k) dst[m][k] = *(const PG8_LAS bf16x8*)(lds + PG8_SA(b, h) + aoff + m * 2048 + k * 1024); } while (0)
; #define PG8_LDB(dst, b, h) do { _Pragma("unroll") for (int n = 0; n < 2; ++n) _Pragma("unroll") for (int k = 0; k < 2; ++k) dst[n][k] = *(const PG8_LAS bf16x8*)(lds + PG8_SB(b, h) + boff + n * 2048 + k * 1024); } while (0)
; #define PG8_MMA(ai, bj, At, Bt) do { __builtin_amdgcn_s_setprio(1); _Pragma("unroll") for (int m = 0; m < 4; ++m) _Pragma("unroll") for (int n = 0; n < 2; ++n) _Pragma("unroll") for (int k = 0; k < 2; ++k) \
;         acc[ai][bj][m][n] = mma16<Epi::F16>(Bt[n][k], At[m][k], acc[ai][bj][m][n]); __builtin_amdgcn_s_setprio(0); } while (0)
; #define PG8_WAIT_V(n) asm volatile("s_waitcnt vmcnt(" #n ")" ::: "memory")
; #define PG8_WAIT_L(n) asm volatile("s_waitcnt lgkmcnt(" #n ")" ::: "memory")
; template <class Epi, class Sched, bool ALIGN_EPI = false, bool SP2 = false>
; __device__ __forceinline__ void gemm_phase(PG8_LAS unsigned char* lds, const Gemm g, const Sched& S, const Epi& E, const int wave_in) {
;     ...
;         for (int t = 0; t < nt; t += 2) {
;             const bool last = (t == nt - 2);
;             const char* a1 = cA + (size_t)(t + 1) * kstep;
;             const char* a2 = last ? nA : cA + (size_t)(t + 2) * kstep; const char* b2 = last ? nB : cB + (size_t)(t + 2) * kstep;
;             const char* a3 = a2 + kstep; const char* b3 = b2 + kstep;
;             if (last && has_next) S.a_ready(nxt);
;             if constexpr (SP2) {
;             PG8_LDB(B0, 0, 0); PG8_LDB(B1, 0, 1); PG8_SCHED; PG8_LDA(At, 0, 0); PG8_STAGE(PG8_SA(1, 1), a1 + hstep, voffA);
;             PG8_WAIT_V(8); PG8_WAIT_L(0); PG8_BAR; PG8_MMA(0, 0, At, B0); PG8_MMA(0, 1, At, B1); PG8_BAR; PG8_SCHED;
;             PG8_LDA(At, 0, 1); PG8_STAGE(PG8_SB(0, 0), b2, voffB); PG8_STAGE(PG8_SB(0, 1), b2 + hstep, voffB); PG8_STAGE(PG8_SA(0, 0), a2, voffA);
;             PG8_WAIT_V(8); PG8_WAIT_L(0); PG8_BAR; PG8_MMA(1, 0, At, B0); PG8_MMA(1, 1, At, B1); PG8_BAR; PG8_SCHED;
.LBB0_1133:
	v_add_u32_e32 v58, s28, v211
	v_add_u32_e32 v78, s72, v211
	ds_read_b128 v[42:45], v58
	ds_read_b128 v[46:49], v58 offset:1024
	ds_read_b128 v[54:57], v58 offset:2048
	ds_read_b128 v[58:61], v58 offset:3072
	ds_read_b128 v[66:69], v78
	ds_read_b128 v[70:73], v78 offset:1024
	ds_read_b128 v[74:77], v78 offset:2048
	ds_read_b128 v[78:81], v78 offset:3072
	s_add_u32 s60, s58, 0x100
	s_addc_u32 s61, s59, 0
	s_cmp_eq_u32 s13, 40
	s_cselect_b32 s63, s45, s61
	s_cselect_b32 s62, s44, s60
	s_cselect_b32 s37, s57, s12
	s_cselect_b32 s36, s56, s11
	v_lshl_add_u64 v[178:179], s[58:59], 0, v[220:221]
	s_add_i32 m0, s1, 0xc000
	ds_read_b128 v[98:101], v213
	ds_read_b128 v[102:105], v213 offset:1024
	ds_read_b128 v[106:109], v213 offset:2048
	ds_read_b128 v[118:121], v213 offset:3072
	ds_read_b128 v[130:133], v213 offset:4096
	ds_read_b128 v[138:141], v213 offset:5120
	ds_read_b128 v[146:149], v213 offset:6144
	ds_read_b128 v[158:161], v213 offset:7168
	global_load_lds_dwordx4 v[178:179], off
	v_lshl_add_u64 v[178:179], s[58:59], 0, v[222:223]
	s_add_i32 m0, s1, 0xe000
	s_nop 0
	global_load_lds_dwordx4 v[178:179], off
	s_waitcnt vmcnt(8)
	s_waitcnt lgkmcnt(0)
	s_barrier
	s_setprio 1
	v_mfma_f32_16x16x32_bf16 v[190:193], v[54:57], v[98:101], v[190:193]
	v_mfma_f32_16x16x32_bf16 v[174:177], v[42:45], v[106:109], v[174:177]
	v_mfma_f32_16x16x32_bf16 v[170:173], v[54:57], v[106:109], v[170:173]
	v_mfma_f32_16x16x32_bf16 v[154:157], v[42:45], v[130:133], v[154:157]
	v_mfma_f32_16x16x32_bf16 v[150:153], v[54:57], v[130:133], v[150:153]
	v_mfma_f32_16x16x32_bf16 v[126:129], v[42:45], v[146:149], v[126:129]
	v_mfma_f32_16x16x32_bf16 v[122:125], v[54:57], v[146:149], v[122:125]
	v_mfma_f32_16x16x32_bf16 v[178:181], v[42:45], v[98:101], v[194:197]
	v_mfma_f32_16x16x32_bf16 v[190:193], v[58:61], v[102:105], v[190:193]
	v_mfma_f32_16x16x32_bf16 v[174:177], v[46:49], v[118:121], v[174:177]
	v_mfma_f32_16x16x32_bf16 v[170:173], v[58:61], v[118:121], v[170:173]
	v_mfma_f32_16x16x32_bf16 v[154:157], v[46:49], v[138:141], v[154:157]
	v_mfma_f32_16x16x32_bf16 v[150:153], v[58:61], v[138:141], v[150:153]
	v_mfma_f32_16x16x32_bf16 v[126:129], v[46:49], v[158:161], v[126:129]
	v_mfma_f32_16x16x32_bf16 v[122:125], v[58:61], v[158:161], v[122:125]
	v_mfma_f32_16x16x32_bf16 v[178:181], v[46:49], v[102:105], v[178:181]
	v_mfma_f32_16x16x32_bf16 v[186:189], v[66:69], v[98:101], v[186:189]
	v_mfma_f32_16x16x32_bf16 v[98:101], v[74:77], v[98:101], v[182:185]
	v_mfma_f32_16x16x32_bf16 v[186:189], v[70:73], v[102:105], v[186:189]
	v_mfma_f32_16x16x32_bf16 v[98:101], v[78:81], v[102:105], v[98:101]
	v_mfma_f32_16x16x32_bf16 v[102:105], v[66:69], v[106:109], v[166:169]
	v_mfma_f32_16x16x32_bf16 v[106:109], v[74:77], v[106:109], v[162:165]
	v_mfma_f32_16x16x32_bf16 v[114:117], v[66:69], v[146:149], v[114:117]
	v_mfma_f32_16x16x32_bf16 v[110:113], v[74:77], v[146:149], v[110:113]
	v_mfma_f32_16x16x32_bf16 v[102:105], v[70:73], v[118:121], v[102:105]
	v_mfma_f32_16x16x32_bf16 v[106:109], v[78:81], v[118:121], v[106:109]
	v_mfma_f32_16x16x32_bf16 v[118:121], v[66:69], v[130:133], v[142:145]
	v_mfma_f32_16x16x32_bf16 v[130:133], v[74:77], v[130:133], v[134:137]
	v_mfma_f32_16x16x32_bf16 v[114:117], v[70:73], v[158:161], v[114:117]
	v_mfma_f32_16x16x32_bf16 v[110:113], v[78:81], v[158:161], v[110:113]
	v_mfma_f32_16x16x32_bf16 v[118:121], v[70:73], v[138:141], v[118:121]
	v_mfma_f32_16x16x32_bf16 v[130:133], v[78:81], v[138:141], v[130:133]
	s_setprio 0
	s_barrier
	s_add_i32 s14, s28, s0
	v_lshl_add_u64 v[228:229], s[36:37], 0, v[0:1]
	s_mov_b32 m0, s14
	ds_read_b128 v[134:137], v213 offset:16384
	ds_read_b128 v[138:141], v213 offset:17408
	ds_read_b128 v[142:145], v213 offset:18432
	ds_read_b128 v[146:149], v213 offset:19456
	ds_read_b128 v[158:161], v213 offset:20480
	ds_read_b128 v[162:165], v213 offset:21504
	ds_read_b128 v[166:169], v213 offset:22528
	ds_read_b128 v[182:185], v213 offset:23552
	global_load_lds_dwordx4 v[228:229], off
	s_add_i32 m0, s14, 0x2000
	s_add_u32 s14, s36, 0xb0000
	v_lshl_add_u64 v[230:231], s[36:37], 0, v[218:219]
	s_addc_u32 s15, s37, 0
	s_add_i32 s16, s72, s0
	global_load_lds_dwordx4 v[230:231], off
	v_lshl_add_u64 v[194:195], s[14:15], 0, v[0:1]
	s_mov_b32 m0, s16
	v_lshl_add_u64 v[232:233], s[62:63], 0, v[214:215]
	global_load_lds_dwordx4 v[194:195], off
	v_lshl_add_u64 v[194:195], s[14:15], 0, v[218:219]
	s_add_i32 m0, s16, 0x2000
	v_lshl_add_u64 v[234:235], s[62:63], 0, v[216:217]
	global_load_lds_dwordx4 v[194:195], off
	s_mov_b32 m0, s1
	s_nop 0
	global_load_lds_dwordx4 v[232:233], off
	s_mov_b32 m0, s4
	s_nop 0
	global_load_lds_dwordx4 v[234:235], off
	s_waitcnt vmcnt(8)
	s_waitcnt lgkmcnt(0)
	s_barrier
; #define PG8_STAGE(bufoff, gbase, voff) do { _Pragma("unroll") for (int _i = 0; _i < 2; ++_i) \
;         __builtin_amdgcn_global_load_lds((const unsigned*)((const char*)(gbase) + (voff)[_i]), (PG8_LAS unsigned*)(lds + (bufoff) + ldsw + _i * 8192), 16, 0, 0); } while (0)
; #define PG8_LDA(dst, b, h) do { _Pragma("unroll") for (int m = 0; m < 4; ++m) _Pragma("unroll") for (int k = 0; k < 2; ++k) dst[m][k] = *(const PG8_LAS bf16x8*)(lds + PG8_SA(b, h) + aoff + m * 2048 + k * 1024); } while (0)
; #define PG8_LDB(dst, b, h) do { _Pragma("unroll") for (int n = 0; n < 2; ++n) _Pragma("unroll") for (int k = 0; k < 2; ++k) dst[n][k] = *(const PG8_LAS bf16x8*)(lds + PG8_SB(b, h) + boff + n * 2048 + k * 1024); } while (0)
; #define PG8_MMA(ai, bj, At, Bt) do { __builtin_amdgcn_s_setprio(1); _Pragma("unroll") for (int m = 0; m < 4; ++m) _Pragma("unroll") for (int n = 0; n < 2; ++n) _Pragma("unroll") for (int k = 0; k < 2; ++k) \
;         acc[ai][bj][m][n] = mma16<Epi::F16>(Bt[n][k], At[m][k], acc[ai][bj][m][n]); __builtin_amdgcn_s_setprio(0); } while (0)
; #define PG8_WAIT_V(n) asm volatile("s_waitcnt vmcnt(" #n ")" ::: "memory")
; #define PG8_WAIT_L(n) asm volatile("s_waitcnt lgkmcnt(" #n ")" ::: "memory")
; #define PG8_BAR __builtin_amdgcn_s_barrier()
; #define PG8_SCHED __builtin_amdgcn_sched_barrier(0)
; template <class Epi, class Sched, bool ALIGN_EPI = false, bool SP2 = false>
; __device__ __forceinline__ void gemm_phase(PG8_LAS unsigned char* lds, const Gemm g, const Sched& S, const Epi& E, const int wave_in) {
;     ...
;             PG8_WAIT_V(8); PG8_WAIT_L(0); PG8_BAR; PG8_MMA(1, 0, At, B0); PG8_MMA(1, 1, At, B1); PG8_BAR; PG8_SCHED;
;             PG8_LDB(B0, 1, 0); PG8_LDB(B1, 1, 1); PG8_SCHED; PG8_LDA(At, 1, 0); PG8_STAGE(PG8_SA(0, 1), a2 + hstep, voffA);
;             PG8_WAIT_V(8); PG8_WAIT_L(0); PG8_BAR; PG8_MMA(0, 0, At, B0); PG8_MMA(0, 1, At, B1); PG8_BAR; PG8_SCHED;
	s_setprio 1
	v_mfma_f32_16x16x32_bf16 v[94:97], v[42:45], v[134:137], v[94:97]
	v_mfma_f32_16x16x32_bf16 v[90:93], v[54:57], v[134:137], v[90:93]
	v_mfma_f32_16x16x32_bf16 v[62:65], v[42:45], v[142:145], v[62:65]
	v_mfma_f32_16x16x32_bf16 v[50:53], v[54:57], v[142:145], v[50:53]
	v_mfma_f32_16x16x32_bf16 v[30:33], v[42:45], v[158:161], v[30:33]
	v_mfma_f32_16x16x32_bf16 v[26:29], v[54:57], v[158:161], v[26:29]
	v_mfma_f32_16x16x32_bf16 v[14:17], v[42:45], v[166:169], v[14:17]
	v_mfma_f32_16x16x32_bf16 v[10:13], v[54:57], v[166:169], v[10:13]
	v_mfma_f32_16x16x32_bf16 v[94:97], v[46:49], v[138:141], v[94:97]
	v_mfma_f32_16x16x32_bf16 v[90:93], v[58:61], v[138:141], v[90:93]
	v_mfma_f32_16x16x32_bf16 v[62:65], v[46:49], v[146:149], v[62:65]
	v_mfma_f32_16x16x32_bf16 v[50:53], v[58:61], v[146:149], v[50:53]
	v_mfma_f32_16x16x32_bf16 v[30:33], v[46:49], v[162:165], v[30:33]
	v_mfma_f32_16x16x32_bf16 v[26:29], v[58:61], v[162:165], v[26:29]
	v_mfma_f32_16x16x32_bf16 v[14:17], v[46:49], v[182:185], v[14:17]
	v_mfma_f32_16x16x32_bf16 v[10:13], v[58:61], v[182:185], v[10:13]
	v_mfma_f32_16x16x32_bf16 v[38:41], v[66:69], v[142:145], v[38:41]
	v_mfma_f32_16x16x32_bf16 v[34:37], v[74:77], v[142:145], v[34:37]
	v_mfma_f32_16x16x32_bf16 v[22:25], v[66:69], v[158:161], v[22:25]
	v_mfma_f32_16x16x32_bf16 v[18:21], v[74:77], v[158:161], v[18:21]
	v_mfma_f32_16x16x32_bf16 v[6:9], v[66:69], v[166:169], v[6:9]
	v_mfma_f32_16x16x32_bf16 v[2:5], v[74:77], v[166:169], v[2:5]
	v_mfma_f32_16x16x32_bf16 v[42:45], v[66:69], v[134:137], v[86:89]
	v_mfma_f32_16x16x32_bf16 v[46:49], v[74:77], v[134:137], v[82:85]
	v_mfma_f32_16x16x32_bf16 v[38:41], v[70:73], v[146:149], v[38:41]
	v_mfma_f32_16x16x32_bf16 v[34:37], v[78:81], v[146:149], v[34:37]
	v_mfma_f32_16x16x32_bf16 v[22:25], v[70:73], v[162:165], v[22:25]
	v_mfma_f32_16x16x32_bf16 v[18:21], v[78:81], v[162:165], v[18:21]
	v_mfma_f32_16x16x32_bf16 v[6:9], v[70:73], v[182:185], v[6:9]
	v_mfma_f32_16x16x32_bf16 v[2:5], v[78:81], v[182:185], v[2:5]
	v_mfma_f32_16x16x32_bf16 v[42:45], v[70:73], v[138:141], v[42:45]
	v_mfma_f32_16x16x32_bf16 v[46:49], v[78:81], v[138:141], v[46:49]
	s_setprio 0
	s_barrier
	v_add_u32_e32 v70, s73, v211
	v_add_u32_e32 v82, s74, v211
	ds_read_b128 v[54:57], v70
	ds_read_b128 v[58:61], v70 offset:1024
	ds_read_b128 v[66:69], v70 offset:2048
	ds_read_b128 v[70:73], v70 offset:3072
	ds_read_b128 v[74:77], v82
	ds_read_b128 v[78:81], v82 offset:1024
	ds_read_b128 v[138:141], v82 offset:2048
	ds_read_b128 v[146:149], v82 offset:3072
	s_add_u32 s14, s62, 0xb0000
	s_addc_u32 s15, s63, 0
	s_mov_b32 m0, s5
	v_lshl_add_u64 v[162:163], s[14:15], 0, v[214:215]
	ds_read_b128 v[82:85], v213 offset:32768
	ds_read_b128 v[86:89], v213 offset:33792
	ds_read_b128 v[134:137], v213 offset:34816
	ds_read_b128 v[142:145], v213 offset:35840
	ds_read_b128 v[158:161], v213 offset:36864
	ds_read_b128 v[198:201], v213 offset:37888
	ds_read_b128 v[202:205], v213 offset:38912
	ds_read_b128 v[224:227], v213 offset:39936
	global_load_lds_dwordx4 v[162:163], off
	v_lshl_add_u64 v[162:163], s[14:15], 0, v[216:217]
	s_mov_b32 m0, s71
	s_nop 0
	global_load_lds_dwordx4 v[162:163], off
	s_waitcnt vmcnt(8)
	s_waitcnt lgkmcnt(0)
	s_barrier
	s_setprio 1
	v_mfma_f32_16x16x32_bf16 v[162:165], v[54:57], v[82:85], v[178:181]
	v_mfma_f32_16x16x32_bf16 v[194:197], v[58:61], v[86:89], v[162:165]
	v_mfma_f32_16x16x32_bf16 v[162:165], v[66:69], v[82:85], v[190:193]
	v_mfma_f32_16x16x32_bf16 v[190:193], v[70:73], v[86:89], v[162:165]
	v_mfma_f32_16x16x32_bf16 v[162:165], v[54:57], v[134:137], v[174:177]
	v_mfma_f32_16x16x32_bf16 v[174:177], v[58:61], v[142:145], v[162:165]
	v_mfma_f32_16x16x32_bf16 v[162:165], v[66:69], v[134:137], v[170:173]
	v_mfma_f32_16x16x32_bf16 v[154:157], v[54:57], v[158:161], v[154:157]
	v_mfma_f32_16x16x32_bf16 v[150:153], v[66:69], v[158:161], v[150:153]
	v_mfma_f32_16x16x32_bf16 v[126:129], v[54:57], v[202:205], v[126:129]
	v_mfma_f32_16x16x32_bf16 v[122:125], v[66:69], v[202:205], v[122:125]
	v_mfma_f32_16x16x32_bf16 v[170:173], v[70:73], v[142:145], v[162:165]
	v_mfma_f32_16x16x32_bf16 v[154:157], v[58:61], v[198:201], v[154:157]
	v_mfma_f32_16x16x32_bf16 v[150:153], v[70:73], v[198:201], v[150:153]
	v_mfma_f32_16x16x32_bf16 v[126:129], v[58:61], v[224:227], v[126:129]
	v_mfma_f32_16x16x32_bf16 v[122:125], v[70:73], v[224:227], v[122:125]
	v_mfma_f32_16x16x32_bf16 v[162:165], v[74:77], v[82:85], v[186:189]
	v_mfma_f32_16x16x32_bf16 v[82:85], v[138:141], v[82:85], v[98:101]
	v_mfma_f32_16x16x32_bf16 v[182:185], v[146:149], v[86:89], v[82:85]
	v_mfma_f32_16x16x32_bf16 v[82:85], v[74:77], v[134:137], v[102:105]
	v_mfma_f32_16x16x32_bf16 v[166:169], v[78:81], v[142:145], v[82:85]
	v_mfma_f32_16x16x32_bf16 v[82:85], v[138:141], v[134:137], v[106:109]
	v_mfma_f32_16x16x32_bf16 v[186:189], v[78:81], v[86:89], v[162:165]
	v_mfma_f32_16x16x32_bf16 v[162:165], v[146:149], v[142:145], v[82:85]
	v_mfma_f32_16x16x32_bf16 v[82:85], v[74:77], v[158:161], v[118:121]
	v_mfma_f32_16x16x32_bf16 v[142:145], v[78:81], v[198:201], v[82:85]
	v_mfma_f32_16x16x32_bf16 v[82:85], v[138:141], v[158:161], v[130:133]
	v_mfma_f32_16x16x32_bf16 v[134:137], v[146:149], v[198:201], v[82:85]
	v_mfma_f32_16x16x32_bf16 v[82:85], v[74:77], v[202:205], v[114:117]
	v_mfma_f32_16x16x32_bf16 v[114:117], v[78:81], v[224:227], v[82:85]
	v_mfma_f32_16x16x32_bf16 v[82:85], v[138:141], v[202:205], v[110:113]
	v_mfma_f32_16x16x32_bf16 v[110:113], v[146:149], v[224:227], v[82:85]
	s_setprio 0
	s_barrier
; #define PG8_STAGE(bufoff, gbase, voff) do { _Pragma("unroll") for (int _i = 0; _i < 2; ++_i) \
;         __builtin_amdgcn_global_load_lds((const unsigned*)((const char*)(gbase) + (voff)[_i]), (PG8_LAS unsigned*)(lds + (bufoff) + ldsw + _i * 8192), 16, 0, 0); } while (0)
; #define PG8_LDA(dst, b, h) do { _Pragma("unroll") for (int m = 0; m < 4; ++m) _Pragma("unroll") for (int k = 0; k < 2; ++k) dst[m][k] = *(const PG8_LAS bf16x8*)(lds + PG8_SA(b, h) + aoff + m * 2048 + k * 1024); } while (0)
; #define PG8_MMA(ai, bj, At, Bt) do { __builtin_amdgcn_s_setprio(1); _Pragma("unroll") for (int m = 0; m < 4; ++m) _Pragma("unroll") for (int n = 0; n < 2; ++n) _Pragma("unroll") for (int k = 0; k < 2; ++k) \
;         acc[ai][bj][m][n] = mma16<Epi::F16>(Bt[n][k], At[m][k], acc[ai][bj][m][n]); __builtin_amdgcn_s_setprio(0); } while (0)
; #define PG8_WAIT_V(n) asm volatile("s_waitcnt vmcnt(" #n ")" ::: "memory")
; #define PG8_WAIT_L(n) asm volatile("s_waitcnt lgkmcnt(" #n ")" ::: "memory")
; #define PG8_BAR __builtin_amdgcn_s_barrier()
; #define PG8_SCHED __builtin_amdgcn_sched_barrier(0)
; template <class Epi, class Sched, bool ALIGN_EPI = false, bool SP2 = false>
; __device__ __forceinline__ void gemm_phase(PG8_LAS unsigned char* lds, const Gemm g, const Sched& S, const Epi& E, const int wave_in) {
;     ...
;         for (int t = 0; t < nt; t += 2) {
;             const bool last = (t == nt - 2);
;             const char* a1 = cA + (size_t)(t + 1) * kstep;
;             const char* a2 = last ? nA : cA + (size_t)(t + 2) * kstep; const char* b2 = last ? nB : cB + (size_t)(t + 2) * kstep;
;             const char* a3 = a2 + kstep; const char* b3 = b2 + kstep;
;     ...
;             PG8_LDA(At, 1, 1); PG8_STAGE(PG8_SB(1, 0), b3, voffB); PG8_STAGE(PG8_SB(1, 1), b3 + hstep, voffB); PG8_STAGE(PG8_SA(1, 0), a3, voffA);
;             PG8_WAIT_V(8); PG8_WAIT_L(0); PG8_BAR; PG8_MMA(1, 0, At, B0); PG8_MMA(1, 1, At, B1); PG8_BAR; PG8_SCHED;
	s_add_i32 s14, s73, s0
	v_lshl_add_u64 v[86:87], v[228:229], 0, s[78:79]
	s_mov_b32 m0, s14
	s_nop 1
	ds_read_b128 v[82:85], v213 offset:49152
	ds_read_b128 v[98:101], v213 offset:50176
	ds_read_b128 v[102:105], v213 offset:51200
	ds_read_b128 v[106:109], v213 offset:52224
	ds_read_b128 v[118:121], v213 offset:53248
	ds_read_b128 v[130:133], v213 offset:54272
	ds_read_b128 v[158:161], v213 offset:55296
	ds_read_b128 v[178:181], v213 offset:56320
	global_load_lds_dwordx4 v[86:87], off
	s_add_i32 m0, s14, 0x2000
	s_add_u32 s14, s36, 0xb0080
	v_lshl_add_u64 v[86:87], v[230:231], 0, s[78:79]
	s_addc_u32 s15, s37, 0
	s_add_i32 s16, s74, s0
	global_load_lds_dwordx4 v[86:87], off
	v_lshl_add_u64 v[86:87], s[14:15], 0, v[0:1]
	s_mov_b32 m0, s16
	s_nop 0
	global_load_lds_dwordx4 v[86:87], off
	v_lshl_add_u64 v[86:87], s[14:15], 0, v[218:219]
	s_add_i32 m0, s16, 0x2000
	s_nop 0
	global_load_lds_dwordx4 v[86:87], off
	v_lshl_add_u64 v[86:87], v[232:233], 0, s[78:79]
	s_mov_b32 m0, s6
	s_nop 0
	global_load_lds_dwordx4 v[86:87], off
	v_lshl_add_u64 v[86:87], v[234:235], 0, s[78:79]
	s_mov_b32 m0, s7
	s_nop 0
	global_load_lds_dwordx4 v[86:87], off
	s_waitcnt vmcnt(8)
	s_waitcnt lgkmcnt(0)
	s_barrier
	s_setprio 1
	v_mfma_f32_16x16x32_bf16 v[86:89], v[54:57], v[82:85], v[94:97]
	v_mfma_f32_16x16x32_bf16 v[94:97], v[58:61], v[98:101], v[86:89]
	v_mfma_f32_16x16x32_bf16 v[86:89], v[66:69], v[82:85], v[90:93]
	v_mfma_f32_16x16x32_bf16 v[62:65], v[54:57], v[102:105], v[62:65]
	v_mfma_f32_16x16x32_bf16 v[50:53], v[66:69], v[102:105], v[50:53]
	v_mfma_f32_16x16x32_bf16 v[30:33], v[54:57], v[118:121], v[30:33]
	v_mfma_f32_16x16x32_bf16 v[26:29], v[66:69], v[118:121], v[26:29]
	v_mfma_f32_16x16x32_bf16 v[14:17], v[54:57], v[158:161], v[14:17]
	v_mfma_f32_16x16x32_bf16 v[10:13], v[66:69], v[158:161], v[10:13]
	v_mfma_f32_16x16x32_bf16 v[90:93], v[70:73], v[98:101], v[86:89]
	v_mfma_f32_16x16x32_bf16 v[62:65], v[58:61], v[106:109], v[62:65]
	v_mfma_f32_16x16x32_bf16 v[50:53], v[70:73], v[106:109], v[50:53]
	v_mfma_f32_16x16x32_bf16 v[30:33], v[58:61], v[130:133], v[30:33]
	v_mfma_f32_16x16x32_bf16 v[26:29], v[70:73], v[130:133], v[26:29]
	v_mfma_f32_16x16x32_bf16 v[14:17], v[58:61], v[178:181], v[14:17]
	v_mfma_f32_16x16x32_bf16 v[10:13], v[70:73], v[178:181], v[10:13]
	v_mfma_f32_16x16x32_bf16 v[42:45], v[74:77], v[82:85], v[42:45]
	v_mfma_f32_16x16x32_bf16 v[86:89], v[78:81], v[98:101], v[42:45]
	v_mfma_f32_16x16x32_bf16 v[42:45], v[138:141], v[82:85], v[46:49]
	v_mfma_f32_16x16x32_bf16 v[38:41], v[74:77], v[102:105], v[38:41]
	v_mfma_f32_16x16x32_bf16 v[34:37], v[138:141], v[102:105], v[34:37]
	v_mfma_f32_16x16x32_bf16 v[22:25], v[74:77], v[118:121], v[22:25]
	v_mfma_f32_16x16x32_bf16 v[18:21], v[138:141], v[118:121], v[18:21]
	v_mfma_f32_16x16x32_bf16 v[6:9], v[74:77], v[158:161], v[6:9]
	v_mfma_f32_16x16x32_bf16 v[2:5], v[138:141], v[158:161], v[2:5]
	v_mfma_f32_16x16x32_bf16 v[82:85], v[146:149], v[98:101], v[42:45]
	v_mfma_f32_16x16x32_bf16 v[38:41], v[78:81], v[106:109], v[38:41]
	v_mfma_f32_16x16x32_bf16 v[34:37], v[146:149], v[106:109], v[34:37]
	v_mfma_f32_16x16x32_bf16 v[22:25], v[78:81], v[130:133], v[22:25]
	v_mfma_f32_16x16x32_bf16 v[18:21], v[146:149], v[130:133], v[18:21]
	v_mfma_f32_16x16x32_bf16 v[6:9], v[78:81], v[178:181], v[6:9]
	v_mfma_f32_16x16x32_bf16 v[2:5], v[146:149], v[178:181], v[2:5]
	s_setprio 0
	s_barrier
	s_add_i32 s13, s13, 2
	s_add_u32 s11, s11, 0x100
	s_addc_u32 s12, s12, 0
	s_cmp_gt_u32 s13, 41
	s_mov_b64 s[58:59], s[60:61]
	s_cbranch_scc0 .LBB0_1133
	s_and_b64 vcc, exec, s[54:55]
	s_cbranch_vccz .LBB0_1136
	s_barrier
